# GEMM K-loops: 8 of the 16 LDS-DMA loads per iteration use SGPR-base + VGPR-offset addressing directly instead of a v_lshl_add_u64 address add in the load segment (on top of v15)
# speedup vs baseline: 1.0016x; 1.0016x over previous
.LBB0_201:
	ds_read_b128 v[144:147], v155
	ds_read_b128 v[148:151], v155 offset:1024
	ds_read_b128 v[158:161], v155 offset:2048
	ds_read_b128 v[162:165], v155 offset:3072
	ds_read_b128 v[166:169], v156
	ds_read_b128 v[170:173], v156 offset:1024
	ds_read_b128 v[174:177], v156 offset:2048
	ds_read_b128 v[178:181], v156 offset:3072
	s_add_u32 s56, s54, 0xfffc0080
	s_addc_u32 s57, s55, -1
	s_cmp_eq_u32 s86, 12
	s_cselect_b32 s59, s11, s57
	s_cselect_b32 s58, s26, s56
	s_cselect_b32 s57, s27, s53
	s_cselect_b32 s56, s45, s47
	s_add_i32 m0, s63, 0xc000
	ds_read_b128 v[182:185], v157
	ds_read_b128 v[186:189], v157 offset:1024
	ds_read_b128 v[190:193], v157 offset:2048
	ds_read_b128 v[194:197], v157 offset:3072
	ds_read_b128 v[198:201], v157 offset:4096
	ds_read_b128 v[202:205], v157 offset:5120
	ds_read_b128 v[206:209], v157 offset:6144
	ds_read_b128 v[210:213], v157 offset:7168
	global_load_lds_dwordx4 v138, s[54:55]
	s_add_i32 m0, s63, 0xe000
	s_nop 0
	global_load_lds_dwordx4 v136, s[54:55]
	s_waitcnt vmcnt(8)
	s_waitcnt lgkmcnt(0)
	s_barrier
	s_setprio 1
	s_waitcnt lgkmcnt(0)
	v_mfma_f32_16x16x32_bf16 v[124:127], v[144:147], v[182:185], v[124:127]
	v_mfma_f32_16x16x32_bf16 v[120:123], v[158:161], v[182:185], v[120:123]
	v_mfma_f32_16x16x32_bf16 v[108:111], v[144:147], v[190:193], v[108:111]
	v_mfma_f32_16x16x32_bf16 v[104:107], v[158:161], v[190:193], v[104:107]
	v_mfma_f32_16x16x32_bf16 v[92:95], v[144:147], v[198:201], v[92:95]
	v_mfma_f32_16x16x32_bf16 v[88:91], v[158:161], v[198:201], v[88:91]
	v_mfma_f32_16x16x32_bf16 v[76:79], v[144:147], v[206:209], v[76:79]
	v_mfma_f32_16x16x32_bf16 v[72:75], v[158:161], v[206:209], v[72:75]
	v_mfma_f32_16x16x32_bf16 v[124:127], v[148:151], v[186:189], v[124:127]
	v_mfma_f32_16x16x32_bf16 v[120:123], v[162:165], v[186:189], v[120:123]
	v_mfma_f32_16x16x32_bf16 v[108:111], v[148:151], v[194:197], v[108:111]
	v_mfma_f32_16x16x32_bf16 v[104:107], v[162:165], v[194:197], v[104:107]
	v_mfma_f32_16x16x32_bf16 v[92:95], v[148:151], v[202:205], v[92:95]
	v_mfma_f32_16x16x32_bf16 v[88:91], v[162:165], v[202:205], v[88:91]
	v_mfma_f32_16x16x32_bf16 v[76:79], v[148:151], v[210:213], v[76:79]
	v_mfma_f32_16x16x32_bf16 v[72:75], v[162:165], v[210:213], v[72:75]
	s_setprio 0
	s_setprio 1
	v_mfma_f32_16x16x32_bf16 v[116:119], v[166:169], v[182:185], v[116:119]
	v_mfma_f32_16x16x32_bf16 v[112:115], v[174:177], v[182:185], v[112:115]
	v_mfma_f32_16x16x32_bf16 v[100:103], v[166:169], v[190:193], v[100:103]
	v_mfma_f32_16x16x32_bf16 v[96:99], v[174:177], v[190:193], v[96:99]
	v_mfma_f32_16x16x32_bf16 v[84:87], v[166:169], v[198:201], v[84:87]
	v_mfma_f32_16x16x32_bf16 v[80:83], v[174:177], v[198:201], v[80:83]
	v_mfma_f32_16x16x32_bf16 v[68:71], v[166:169], v[206:209], v[68:71]
	v_mfma_f32_16x16x32_bf16 v[64:67], v[174:177], v[206:209], v[64:67]
	v_mfma_f32_16x16x32_bf16 v[116:119], v[170:173], v[186:189], v[116:119]
	v_mfma_f32_16x16x32_bf16 v[112:115], v[178:181], v[186:189], v[112:115]
	v_mfma_f32_16x16x32_bf16 v[100:103], v[170:173], v[194:197], v[100:103]
	v_mfma_f32_16x16x32_bf16 v[96:99], v[178:181], v[194:197], v[96:99]
	v_mfma_f32_16x16x32_bf16 v[84:87], v[170:173], v[202:205], v[84:87]
	v_mfma_f32_16x16x32_bf16 v[80:83], v[178:181], v[202:205], v[80:83]
	v_mfma_f32_16x16x32_bf16 v[68:71], v[170:173], v[210:213], v[68:71]
	v_mfma_f32_16x16x32_bf16 v[64:67], v[178:181], v[210:213], v[64:67]
	s_setprio 0
	s_barrier
	s_add_i32 s70, s83, s60
	v_lshl_add_u64 v[214:215], s[56:57], 0, v[130:131]
	s_mov_b32 m0, s70
	ds_read_b128 v[182:185], v157 offset:16384
	ds_read_b128 v[186:189], v157 offset:17408
	ds_read_b128 v[190:193], v157 offset:18432
	ds_read_b128 v[194:197], v157 offset:19456
	ds_read_b128 v[198:201], v157 offset:20480
	ds_read_b128 v[202:205], v157 offset:21504
	ds_read_b128 v[206:209], v157 offset:22528
	ds_read_b128 v[210:213], v157 offset:23552
	global_load_lds_dwordx4 v[214:215], off
	s_add_i32 m0, s70, 0x2000
	s_add_u32 s88, s56, 0x40000
	v_lshl_add_u64 v[216:217], s[56:57], 0, v[134:135]
	s_addc_u32 s89, s57, 0
	s_add_i32 s70, s84, s60
	global_load_lds_dwordx4 v[216:217], off
	s_mov_b32 m0, s70
	v_lshl_add_u64 v[220:221], s[58:59], 0, v[132:133]
	global_load_lds_dwordx4 v130, s[88:89]
	s_add_i32 m0, s70, 0x2000
	s_nop 0
	global_load_lds_dwordx4 v134, s[88:89]
	v_lshl_add_u64 v[218:219], s[58:59], 0, v[128:129]
	s_mov_b32 m0, s63
	s_nop 0
	global_load_lds_dwordx4 v[218:219], off
	s_mov_b32 m0, s67
	s_nop 0
	global_load_lds_dwordx4 v[220:221], off
	s_waitcnt vmcnt(8)
	s_waitcnt lgkmcnt(0)
	s_barrier
	s_setprio 1
	s_waitcnt lgkmcnt(0)
	v_mfma_f32_16x16x32_bf16 v[60:63], v[144:147], v[182:185], v[60:63]
	v_mfma_f32_16x16x32_bf16 v[56:59], v[158:161], v[182:185], v[56:59]
	v_mfma_f32_16x16x32_bf16 v[44:47], v[144:147], v[190:193], v[44:47]
	v_mfma_f32_16x16x32_bf16 v[40:43], v[158:161], v[190:193], v[40:43]
	v_mfma_f32_16x16x32_bf16 v[28:31], v[144:147], v[198:201], v[28:31]
	v_mfma_f32_16x16x32_bf16 v[24:27], v[158:161], v[198:201], v[24:27]
	v_mfma_f32_16x16x32_bf16 v[12:15], v[144:147], v[206:209], v[12:15]
	v_mfma_f32_16x16x32_bf16 v[8:11], v[158:161], v[206:209], v[8:11]
	v_mfma_f32_16x16x32_bf16 v[60:63], v[148:151], v[186:189], v[60:63]
	v_mfma_f32_16x16x32_bf16 v[56:59], v[162:165], v[186:189], v[56:59]
	v_mfma_f32_16x16x32_bf16 v[44:47], v[148:151], v[194:197], v[44:47]
	v_mfma_f32_16x16x32_bf16 v[40:43], v[162:165], v[194:197], v[40:43]
	v_mfma_f32_16x16x32_bf16 v[28:31], v[148:151], v[202:205], v[28:31]
	v_mfma_f32_16x16x32_bf16 v[24:27], v[162:165], v[202:205], v[24:27]
	v_mfma_f32_16x16x32_bf16 v[12:15], v[148:151], v[210:213], v[12:15]
	v_mfma_f32_16x16x32_bf16 v[8:11], v[162:165], v[210:213], v[8:11]
	s_setprio 0
	s_setprio 1
	v_mfma_f32_16x16x32_bf16 v[52:55], v[166:169], v[182:185], v[52:55]
	v_mfma_f32_16x16x32_bf16 v[48:51], v[174:177], v[182:185], v[48:51]
	v_mfma_f32_16x16x32_bf16 v[36:39], v[166:169], v[190:193], v[36:39]
	v_mfma_f32_16x16x32_bf16 v[32:35], v[174:177], v[190:193], v[32:35]
	v_mfma_f32_16x16x32_bf16 v[20:23], v[166:169], v[198:201], v[20:23]
	v_mfma_f32_16x16x32_bf16 v[16:19], v[174:177], v[198:201], v[16:19]
	v_mfma_f32_16x16x32_bf16 v[4:7], v[166:169], v[206:209], v[4:7]
	v_mfma_f32_16x16x32_bf16 v[0:3], v[174:177], v[206:209], v[0:3]
	v_mfma_f32_16x16x32_bf16 v[52:55], v[170:173], v[186:189], v[52:55]
	v_mfma_f32_16x16x32_bf16 v[48:51], v[178:181], v[186:189], v[48:51]
	v_mfma_f32_16x16x32_bf16 v[36:39], v[170:173], v[194:197], v[36:39]
	v_mfma_f32_16x16x32_bf16 v[32:35], v[178:181], v[194:197], v[32:35]
	v_mfma_f32_16x16x32_bf16 v[20:23], v[170:173], v[202:205], v[20:23]
	v_mfma_f32_16x16x32_bf16 v[16:19], v[178:181], v[202:205], v[16:19]
	v_mfma_f32_16x16x32_bf16 v[4:7], v[170:173], v[210:213], v[4:7]
	v_mfma_f32_16x16x32_bf16 v[0:3], v[178:181], v[210:213], v[0:3]
	s_setprio 0
	s_barrier
	s_add_i32 s70, 0, 0x18000
	s_add_i32 s87, 0, 0x1c000
	v_add_u32_e32 v162, s70, v154
	v_add_u32_e32 v178, s87, v154
	ds_read_b128 v[144:147], v162
	ds_read_b128 v[148:151], v162 offset:1024
	ds_read_b128 v[158:161], v162 offset:2048
	ds_read_b128 v[162:165], v162 offset:3072
	ds_read_b128 v[166:169], v178
	ds_read_b128 v[170:173], v178 offset:1024
	ds_read_b128 v[174:177], v178 offset:2048
	ds_read_b128 v[178:181], v178 offset:3072
	s_add_u32 s58, s58, 0x40000
	s_addc_u32 s59, s59, 0
	s_mov_b32 m0, s68
	ds_read_b128 v[182:185], v157 offset:32768
	ds_read_b128 v[186:189], v157 offset:33792
	ds_read_b128 v[190:193], v157 offset:34816
	ds_read_b128 v[194:197], v157 offset:35840
	ds_read_b128 v[198:201], v157 offset:36864
	ds_read_b128 v[202:205], v157 offset:37888
	ds_read_b128 v[206:209], v157 offset:38912
	ds_read_b128 v[210:213], v157 offset:39936
	global_load_lds_dwordx4 v128, s[58:59]
	s_mov_b32 m0, s69
	s_nop 0
	global_load_lds_dwordx4 v132, s[58:59]
	s_waitcnt vmcnt(8)
	s_waitcnt lgkmcnt(0)
	s_barrier
	s_setprio 1
	s_waitcnt lgkmcnt(0)
	v_mfma_f32_16x16x32_bf16 v[124:127], v[144:147], v[182:185], v[124:127]
	v_mfma_f32_16x16x32_bf16 v[120:123], v[158:161], v[182:185], v[120:123]
	v_mfma_f32_16x16x32_bf16 v[108:111], v[144:147], v[190:193], v[108:111]
	v_mfma_f32_16x16x32_bf16 v[104:107], v[158:161], v[190:193], v[104:107]
	v_mfma_f32_16x16x32_bf16 v[92:95], v[144:147], v[198:201], v[92:95]
	v_mfma_f32_16x16x32_bf16 v[88:91], v[158:161], v[198:201], v[88:91]
	v_mfma_f32_16x16x32_bf16 v[76:79], v[144:147], v[206:209], v[76:79]
	v_mfma_f32_16x16x32_bf16 v[72:75], v[158:161], v[206:209], v[72:75]
	v_mfma_f32_16x16x32_bf16 v[124:127], v[148:151], v[186:189], v[124:127]
	v_mfma_f32_16x16x32_bf16 v[120:123], v[162:165], v[186:189], v[120:123]
	v_mfma_f32_16x16x32_bf16 v[108:111], v[148:151], v[194:197], v[108:111]
	v_mfma_f32_16x16x32_bf16 v[104:107], v[162:165], v[194:197], v[104:107]
	v_mfma_f32_16x16x32_bf16 v[92:95], v[148:151], v[202:205], v[92:95]
	v_mfma_f32_16x16x32_bf16 v[88:91], v[162:165], v[202:205], v[88:91]
	v_mfma_f32_16x16x32_bf16 v[76:79], v[148:151], v[210:213], v[76:79]
	v_mfma_f32_16x16x32_bf16 v[72:75], v[162:165], v[210:213], v[72:75]
	s_setprio 0
	s_setprio 1
	v_mfma_f32_16x16x32_bf16 v[116:119], v[166:169], v[182:185], v[116:119]
	v_mfma_f32_16x16x32_bf16 v[112:115], v[174:177], v[182:185], v[112:115]
	v_mfma_f32_16x16x32_bf16 v[100:103], v[166:169], v[190:193], v[100:103]
	v_mfma_f32_16x16x32_bf16 v[96:99], v[174:177], v[190:193], v[96:99]
	v_mfma_f32_16x16x32_bf16 v[84:87], v[166:169], v[198:201], v[84:87]
	v_mfma_f32_16x16x32_bf16 v[80:83], v[174:177], v[198:201], v[80:83]
	v_mfma_f32_16x16x32_bf16 v[68:71], v[166:169], v[206:209], v[68:71]
	v_mfma_f32_16x16x32_bf16 v[64:67], v[174:177], v[206:209], v[64:67]
	v_mfma_f32_16x16x32_bf16 v[116:119], v[170:173], v[186:189], v[116:119]
	v_mfma_f32_16x16x32_bf16 v[112:115], v[178:181], v[186:189], v[112:115]
	v_mfma_f32_16x16x32_bf16 v[100:103], v[170:173], v[194:197], v[100:103]
	v_mfma_f32_16x16x32_bf16 v[96:99], v[178:181], v[194:197], v[96:99]
	v_mfma_f32_16x16x32_bf16 v[84:87], v[170:173], v[202:205], v[84:87]
	v_mfma_f32_16x16x32_bf16 v[80:83], v[178:181], v[202:205], v[80:83]
	v_mfma_f32_16x16x32_bf16 v[68:71], v[170:173], v[210:213], v[68:71]
	v_mfma_f32_16x16x32_bf16 v[64:67], v[178:181], v[210:213], v[64:67]
	s_setprio 0
	s_barrier
	s_add_i32 s58, s70, s60
	v_lshl_add_u64 v[214:215], v[214:215], 0, s[18:19]
	s_mov_b32 m0, s58
	ds_read_b128 v[182:185], v157 offset:49152
	ds_read_b128 v[186:189], v157 offset:50176
	ds_read_b128 v[190:193], v157 offset:51200
	ds_read_b128 v[194:197], v157 offset:52224
	ds_read_b128 v[198:201], v157 offset:53248
	ds_read_b128 v[202:205], v157 offset:54272
	ds_read_b128 v[206:209], v157 offset:55296
	ds_read_b128 v[210:213], v157 offset:56320
	global_load_lds_dwordx4 v[214:215], off
	s_add_i32 m0, s58, 0x2000
	s_add_u32 s56, s56, 0x40080
	v_lshl_add_u64 v[214:215], v[216:217], 0, s[18:19]
	s_addc_u32 s57, s57, 0
	s_add_i32 s58, s87, s60
	global_load_lds_dwordx4 v[214:215], off
	s_mov_b32 m0, s58
	s_nop 0
	global_load_lds_dwordx4 v130, s[56:57]
	s_add_i32 m0, s58, 0x2000
	s_nop 0
	global_load_lds_dwordx4 v134, s[56:57]
	v_lshl_add_u64 v[214:215], v[218:219], 0, s[18:19]
	s_mov_b32 m0, s80
	s_nop 0
	global_load_lds_dwordx4 v[214:215], off
	v_lshl_add_u64 v[214:215], v[220:221], 0, s[18:19]
	s_mov_b32 m0, s81
	s_nop 0
	global_load_lds_dwordx4 v[214:215], off
	s_waitcnt vmcnt(8)
	s_waitcnt lgkmcnt(0)
	s_barrier
	s_setprio 1
	s_waitcnt lgkmcnt(0)
	v_mfma_f32_16x16x32_bf16 v[60:63], v[144:147], v[182:185], v[60:63]
	v_mfma_f32_16x16x32_bf16 v[56:59], v[158:161], v[182:185], v[56:59]
	v_mfma_f32_16x16x32_bf16 v[44:47], v[144:147], v[190:193], v[44:47]
	v_mfma_f32_16x16x32_bf16 v[40:43], v[158:161], v[190:193], v[40:43]
	v_mfma_f32_16x16x32_bf16 v[28:31], v[144:147], v[198:201], v[28:31]
	v_mfma_f32_16x16x32_bf16 v[24:27], v[158:161], v[198:201], v[24:27]
	v_mfma_f32_16x16x32_bf16 v[12:15], v[144:147], v[206:209], v[12:15]
	v_mfma_f32_16x16x32_bf16 v[8:11], v[158:161], v[206:209], v[8:11]
	v_mfma_f32_16x16x32_bf16 v[60:63], v[148:151], v[186:189], v[60:63]
	v_mfma_f32_16x16x32_bf16 v[56:59], v[162:165], v[186:189], v[56:59]
	v_mfma_f32_16x16x32_bf16 v[44:47], v[148:151], v[194:197], v[44:47]
	v_mfma_f32_16x16x32_bf16 v[40:43], v[162:165], v[194:197], v[40:43]
	v_mfma_f32_16x16x32_bf16 v[28:31], v[148:151], v[202:205], v[28:31]
	v_mfma_f32_16x16x32_bf16 v[24:27], v[162:165], v[202:205], v[24:27]
	v_mfma_f32_16x16x32_bf16 v[12:15], v[148:151], v[210:213], v[12:15]
	v_mfma_f32_16x16x32_bf16 v[8:11], v[162:165], v[210:213], v[8:11]
	s_setprio 0
	s_setprio 1
	v_mfma_f32_16x16x32_bf16 v[52:55], v[166:169], v[182:185], v[52:55]
	v_mfma_f32_16x16x32_bf16 v[48:51], v[174:177], v[182:185], v[48:51]
	v_mfma_f32_16x16x32_bf16 v[36:39], v[166:169], v[190:193], v[36:39]
	v_mfma_f32_16x16x32_bf16 v[32:35], v[174:177], v[190:193], v[32:35]
	v_mfma_f32_16x16x32_bf16 v[20:23], v[166:169], v[198:201], v[20:23]
	v_mfma_f32_16x16x32_bf16 v[16:19], v[174:177], v[198:201], v[16:19]
	v_mfma_f32_16x16x32_bf16 v[4:7], v[166:169], v[206:209], v[4:7]
	v_mfma_f32_16x16x32_bf16 v[0:3], v[174:177], v[206:209], v[0:3]
	v_mfma_f32_16x16x32_bf16 v[52:55], v[170:173], v[186:189], v[52:55]
	v_mfma_f32_16x16x32_bf16 v[48:51], v[178:181], v[186:189], v[48:51]
	v_mfma_f32_16x16x32_bf16 v[36:39], v[170:173], v[194:197], v[36:39]
	v_mfma_f32_16x16x32_bf16 v[32:35], v[178:181], v[194:197], v[32:35]
	v_mfma_f32_16x16x32_bf16 v[20:23], v[170:173], v[202:205], v[20:23]
	v_mfma_f32_16x16x32_bf16 v[16:19], v[178:181], v[202:205], v[16:19]
	v_mfma_f32_16x16x32_bf16 v[4:7], v[170:173], v[210:213], v[4:7]
	v_mfma_f32_16x16x32_bf16 v[0:3], v[178:181], v[210:213], v[0:3]
	s_setprio 0
	s_barrier
	s_add_i32 s86, s86, 2
	s_add_u32 s47, s47, 0x100
	s_addc_u32 s53, s53, 0
	s_add_u32 s54, s54, 0x100
	s_addc_u32 s55, s55, 0
	s_cmp_gt_u32 s86, 13
	s_cbranch_scc0 .LBB0_201
	s_and_b64 vcc, exec, s[42:43]
	s_cbranch_vccz .LBB0_204
	s_barrier

.LBB0_733:
	ds_read_b128 v[144:147], v151
	ds_read_b128 v[154:157], v151 offset:1024
	ds_read_b128 v[158:161], v151 offset:2048
	ds_read_b128 v[162:165], v151 offset:3072
	ds_read_b128 v[166:169], v152
	ds_read_b128 v[170:173], v152 offset:1024
	ds_read_b128 v[174:177], v152 offset:2048
	ds_read_b128 v[178:181], v152 offset:3072
	s_add_u32 s22, s46, 0xfffc0080
	s_addc_u32 s23, s47, -1
	s_cmp_eq_u32 s71, 12
	s_cselect_b32 s51, s26, s23
	s_cselect_b32 s50, s27, s22
	s_cselect_b32 s49, s39, s69
	s_cselect_b32 s48, s41, s68
	s_add_i32 m0, s13, 0xc000
	ds_read_b128 v[182:185], v153
	ds_read_b128 v[186:189], v153 offset:1024
	ds_read_b128 v[190:193], v153 offset:2048
	ds_read_b128 v[194:197], v153 offset:3072
	ds_read_b128 v[198:201], v153 offset:4096
	ds_read_b128 v[202:205], v153 offset:5120
	ds_read_b128 v[206:209], v153 offset:6144
	ds_read_b128 v[210:213], v153 offset:7168
	global_load_lds_dwordx4 v138, s[46:47]
	s_add_i32 m0, s13, 0xe000
	s_nop 0
	global_load_lds_dwordx4 v136, s[46:47]
	s_waitcnt vmcnt(8)
	s_waitcnt lgkmcnt(0)
	s_barrier
	s_setprio 1
	s_waitcnt lgkmcnt(0)
	v_mfma_f32_16x16x32_bf16 v[124:127], v[144:147], v[182:185], v[124:127]
	v_mfma_f32_16x16x32_bf16 v[120:123], v[158:161], v[182:185], v[120:123]
	v_mfma_f32_16x16x32_bf16 v[108:111], v[144:147], v[190:193], v[108:111]
	v_mfma_f32_16x16x32_bf16 v[104:107], v[158:161], v[190:193], v[104:107]
	v_mfma_f32_16x16x32_bf16 v[92:95], v[144:147], v[198:201], v[92:95]
	v_mfma_f32_16x16x32_bf16 v[88:91], v[158:161], v[198:201], v[88:91]
	v_mfma_f32_16x16x32_bf16 v[76:79], v[144:147], v[206:209], v[76:79]
	v_mfma_f32_16x16x32_bf16 v[72:75], v[158:161], v[206:209], v[72:75]
	v_mfma_f32_16x16x32_bf16 v[124:127], v[154:157], v[186:189], v[124:127]
	v_mfma_f32_16x16x32_bf16 v[120:123], v[162:165], v[186:189], v[120:123]
	v_mfma_f32_16x16x32_bf16 v[108:111], v[154:157], v[194:197], v[108:111]
	v_mfma_f32_16x16x32_bf16 v[104:107], v[162:165], v[194:197], v[104:107]
	v_mfma_f32_16x16x32_bf16 v[92:95], v[154:157], v[202:205], v[92:95]
	v_mfma_f32_16x16x32_bf16 v[88:91], v[162:165], v[202:205], v[88:91]
	v_mfma_f32_16x16x32_bf16 v[76:79], v[154:157], v[210:213], v[76:79]
	v_mfma_f32_16x16x32_bf16 v[72:75], v[162:165], v[210:213], v[72:75]
	s_setprio 0
	s_setprio 1
	v_mfma_f32_16x16x32_bf16 v[116:119], v[166:169], v[182:185], v[116:119]
	v_mfma_f32_16x16x32_bf16 v[112:115], v[174:177], v[182:185], v[112:115]
	v_mfma_f32_16x16x32_bf16 v[100:103], v[166:169], v[190:193], v[100:103]
	v_mfma_f32_16x16x32_bf16 v[96:99], v[174:177], v[190:193], v[96:99]
	v_mfma_f32_16x16x32_bf16 v[84:87], v[166:169], v[198:201], v[84:87]
	v_mfma_f32_16x16x32_bf16 v[80:83], v[174:177], v[198:201], v[80:83]
	v_mfma_f32_16x16x32_bf16 v[68:71], v[166:169], v[206:209], v[68:71]
	v_mfma_f32_16x16x32_bf16 v[64:67], v[174:177], v[206:209], v[64:67]
	v_mfma_f32_16x16x32_bf16 v[116:119], v[170:173], v[186:189], v[116:119]
	v_mfma_f32_16x16x32_bf16 v[112:115], v[178:181], v[186:189], v[112:115]
	v_mfma_f32_16x16x32_bf16 v[100:103], v[170:173], v[194:197], v[100:103]
	v_mfma_f32_16x16x32_bf16 v[96:99], v[178:181], v[194:197], v[96:99]
	v_mfma_f32_16x16x32_bf16 v[84:87], v[170:173], v[202:205], v[84:87]
	v_mfma_f32_16x16x32_bf16 v[80:83], v[178:181], v[202:205], v[80:83]
	v_mfma_f32_16x16x32_bf16 v[68:71], v[170:173], v[210:213], v[68:71]
	v_mfma_f32_16x16x32_bf16 v[64:67], v[178:181], v[210:213], v[64:67]
	s_setprio 0
	s_barrier
	s_add_i32 s22, s65, s56
	v_lshl_add_u64 v[214:215], s[48:49], 0, v[130:131]
	s_mov_b32 m0, s22
	ds_read_b128 v[182:185], v153 offset:16384
	ds_read_b128 v[186:189], v153 offset:17408
	ds_read_b128 v[190:193], v153 offset:18432
	ds_read_b128 v[194:197], v153 offset:19456
	ds_read_b128 v[198:201], v153 offset:20480
	ds_read_b128 v[202:205], v153 offset:21504
	ds_read_b128 v[206:209], v153 offset:22528
	ds_read_b128 v[210:213], v153 offset:23552
	global_load_lds_dwordx4 v[214:215], off
	s_add_i32 m0, s22, 0x2000
	s_add_u32 s80, s48, 0x40000
	v_lshl_add_u64 v[216:217], s[48:49], 0, v[134:135]
	s_addc_u32 s81, s49, 0
	s_add_i32 s22, s66, s56
	global_load_lds_dwordx4 v[216:217], off
	s_mov_b32 m0, s22
	v_lshl_add_u64 v[220:221], s[50:51], 0, v[132:133]
	global_load_lds_dwordx4 v130, s[80:81]
	s_add_i32 m0, s22, 0x2000
	s_nop 0
	global_load_lds_dwordx4 v134, s[80:81]
	v_lshl_add_u64 v[218:219], s[50:51], 0, v[128:129]
	s_mov_b32 m0, s13
	s_nop 0
	global_load_lds_dwordx4 v[218:219], off
	s_mov_b32 m0, s57
	s_nop 0
	global_load_lds_dwordx4 v[220:221], off
	s_waitcnt vmcnt(8)
	s_waitcnt lgkmcnt(0)
	s_barrier
	s_setprio 1
	s_waitcnt lgkmcnt(0)
	v_mfma_f32_16x16x32_bf16 v[60:63], v[144:147], v[182:185], v[60:63]
	v_mfma_f32_16x16x32_bf16 v[56:59], v[158:161], v[182:185], v[56:59]
	v_mfma_f32_16x16x32_bf16 v[44:47], v[144:147], v[190:193], v[44:47]
	v_mfma_f32_16x16x32_bf16 v[40:43], v[158:161], v[190:193], v[40:43]
	v_mfma_f32_16x16x32_bf16 v[28:31], v[144:147], v[198:201], v[28:31]
	v_mfma_f32_16x16x32_bf16 v[24:27], v[158:161], v[198:201], v[24:27]
	v_mfma_f32_16x16x32_bf16 v[12:15], v[144:147], v[206:209], v[12:15]
	v_mfma_f32_16x16x32_bf16 v[8:11], v[158:161], v[206:209], v[8:11]
	v_mfma_f32_16x16x32_bf16 v[60:63], v[154:157], v[186:189], v[60:63]
	v_mfma_f32_16x16x32_bf16 v[56:59], v[162:165], v[186:189], v[56:59]
	v_mfma_f32_16x16x32_bf16 v[44:47], v[154:157], v[194:197], v[44:47]
	v_mfma_f32_16x16x32_bf16 v[40:43], v[162:165], v[194:197], v[40:43]
	v_mfma_f32_16x16x32_bf16 v[28:31], v[154:157], v[202:205], v[28:31]
	v_mfma_f32_16x16x32_bf16 v[24:27], v[162:165], v[202:205], v[24:27]
	v_mfma_f32_16x16x32_bf16 v[12:15], v[154:157], v[210:213], v[12:15]
	v_mfma_f32_16x16x32_bf16 v[8:11], v[162:165], v[210:213], v[8:11]
	s_setprio 0
	s_setprio 1
	v_mfma_f32_16x16x32_bf16 v[52:55], v[166:169], v[182:185], v[52:55]
	v_mfma_f32_16x16x32_bf16 v[48:51], v[174:177], v[182:185], v[48:51]
	v_mfma_f32_16x16x32_bf16 v[36:39], v[166:169], v[190:193], v[36:39]
	v_mfma_f32_16x16x32_bf16 v[32:35], v[174:177], v[190:193], v[32:35]
	v_mfma_f32_16x16x32_bf16 v[20:23], v[166:169], v[198:201], v[20:23]
	v_mfma_f32_16x16x32_bf16 v[16:19], v[174:177], v[198:201], v[16:19]
	v_mfma_f32_16x16x32_bf16 v[4:7], v[166:169], v[206:209], v[4:7]
	v_mfma_f32_16x16x32_bf16 v[0:3], v[174:177], v[206:209], v[0:3]
	v_mfma_f32_16x16x32_bf16 v[52:55], v[170:173], v[186:189], v[52:55]
	v_mfma_f32_16x16x32_bf16 v[48:51], v[178:181], v[186:189], v[48:51]
	v_mfma_f32_16x16x32_bf16 v[36:39], v[170:173], v[194:197], v[36:39]
	v_mfma_f32_16x16x32_bf16 v[32:35], v[178:181], v[194:197], v[32:35]
	v_mfma_f32_16x16x32_bf16 v[20:23], v[170:173], v[202:205], v[20:23]
	v_mfma_f32_16x16x32_bf16 v[16:19], v[178:181], v[202:205], v[16:19]
	v_mfma_f32_16x16x32_bf16 v[4:7], v[170:173], v[210:213], v[4:7]
	v_mfma_f32_16x16x32_bf16 v[0:3], v[178:181], v[210:213], v[0:3]
	s_setprio 0
	s_barrier
	s_add_i32 s22, 0, 0x18000
	s_add_i32 s23, 0, 0x1c000
	v_add_u32_e32 v162, s22, v150
	v_add_u32_e32 v178, s23, v150
	ds_read_b128 v[144:147], v162
	ds_read_b128 v[154:157], v162 offset:1024
	ds_read_b128 v[158:161], v162 offset:2048
	ds_read_b128 v[162:165], v162 offset:3072
	ds_read_b128 v[166:169], v178
	ds_read_b128 v[170:173], v178 offset:1024
	ds_read_b128 v[174:177], v178 offset:2048
	ds_read_b128 v[178:181], v178 offset:3072
	s_add_u32 s50, s50, 0x40000
	s_addc_u32 s51, s51, 0
	s_mov_b32 m0, s58
	ds_read_b128 v[182:185], v153 offset:32768
	ds_read_b128 v[186:189], v153 offset:33792
	ds_read_b128 v[190:193], v153 offset:34816
	ds_read_b128 v[194:197], v153 offset:35840
	ds_read_b128 v[198:201], v153 offset:36864
	ds_read_b128 v[202:205], v153 offset:37888
	ds_read_b128 v[206:209], v153 offset:38912
	ds_read_b128 v[210:213], v153 offset:39936
	global_load_lds_dwordx4 v128, s[50:51]
	s_mov_b32 m0, s59
	s_nop 0
	global_load_lds_dwordx4 v132, s[50:51]
	s_waitcnt vmcnt(8)
	s_waitcnt lgkmcnt(0)
	s_barrier
	s_setprio 1
	s_waitcnt lgkmcnt(0)
	v_mfma_f32_16x16x32_bf16 v[124:127], v[144:147], v[182:185], v[124:127]
	v_mfma_f32_16x16x32_bf16 v[120:123], v[158:161], v[182:185], v[120:123]
	v_mfma_f32_16x16x32_bf16 v[108:111], v[144:147], v[190:193], v[108:111]
	v_mfma_f32_16x16x32_bf16 v[104:107], v[158:161], v[190:193], v[104:107]
	v_mfma_f32_16x16x32_bf16 v[92:95], v[144:147], v[198:201], v[92:95]
	v_mfma_f32_16x16x32_bf16 v[88:91], v[158:161], v[198:201], v[88:91]
	v_mfma_f32_16x16x32_bf16 v[76:79], v[144:147], v[206:209], v[76:79]
	v_mfma_f32_16x16x32_bf16 v[72:75], v[158:161], v[206:209], v[72:75]
	v_mfma_f32_16x16x32_bf16 v[124:127], v[154:157], v[186:189], v[124:127]
	v_mfma_f32_16x16x32_bf16 v[120:123], v[162:165], v[186:189], v[120:123]
	v_mfma_f32_16x16x32_bf16 v[108:111], v[154:157], v[194:197], v[108:111]
	v_mfma_f32_16x16x32_bf16 v[104:107], v[162:165], v[194:197], v[104:107]
	v_mfma_f32_16x16x32_bf16 v[92:95], v[154:157], v[202:205], v[92:95]
	v_mfma_f32_16x16x32_bf16 v[88:91], v[162:165], v[202:205], v[88:91]
	v_mfma_f32_16x16x32_bf16 v[76:79], v[154:157], v[210:213], v[76:79]
	v_mfma_f32_16x16x32_bf16 v[72:75], v[162:165], v[210:213], v[72:75]
	s_setprio 0
	s_setprio 1
	v_mfma_f32_16x16x32_bf16 v[116:119], v[166:169], v[182:185], v[116:119]
	v_mfma_f32_16x16x32_bf16 v[112:115], v[174:177], v[182:185], v[112:115]
	v_mfma_f32_16x16x32_bf16 v[100:103], v[166:169], v[190:193], v[100:103]
	v_mfma_f32_16x16x32_bf16 v[96:99], v[174:177], v[190:193], v[96:99]
	v_mfma_f32_16x16x32_bf16 v[84:87], v[166:169], v[198:201], v[84:87]
	v_mfma_f32_16x16x32_bf16 v[80:83], v[174:177], v[198:201], v[80:83]
	v_mfma_f32_16x16x32_bf16 v[68:71], v[166:169], v[206:209], v[68:71]
	v_mfma_f32_16x16x32_bf16 v[64:67], v[174:177], v[206:209], v[64:67]
	v_mfma_f32_16x16x32_bf16 v[116:119], v[170:173], v[186:189], v[116:119]
	v_mfma_f32_16x16x32_bf16 v[112:115], v[178:181], v[186:189], v[112:115]
	v_mfma_f32_16x16x32_bf16 v[100:103], v[170:173], v[194:197], v[100:103]
	v_mfma_f32_16x16x32_bf16 v[96:99], v[178:181], v[194:197], v[96:99]
	v_mfma_f32_16x16x32_bf16 v[84:87], v[170:173], v[202:205], v[84:87]
	v_mfma_f32_16x16x32_bf16 v[80:83], v[178:181], v[202:205], v[80:83]
	v_mfma_f32_16x16x32_bf16 v[68:71], v[170:173], v[210:213], v[68:71]
	v_mfma_f32_16x16x32_bf16 v[64:67], v[178:181], v[210:213], v[64:67]
	s_setprio 0
	s_barrier
	s_add_i32 s22, s22, s56
	v_lshl_add_u64 v[214:215], v[214:215], 0, s[34:35]
	s_mov_b32 m0, s22
	ds_read_b128 v[182:185], v153 offset:49152
	ds_read_b128 v[186:189], v153 offset:50176
	ds_read_b128 v[190:193], v153 offset:51200
	ds_read_b128 v[194:197], v153 offset:52224
	ds_read_b128 v[198:201], v153 offset:53248
	ds_read_b128 v[202:205], v153 offset:54272
	ds_read_b128 v[206:209], v153 offset:55296
	ds_read_b128 v[210:213], v153 offset:56320
	global_load_lds_dwordx4 v[214:215], off
	s_add_i32 m0, s22, 0x2000
	s_add_u32 s48, s48, 0x40080
	v_lshl_add_u64 v[214:215], v[216:217], 0, s[34:35]
	s_addc_u32 s49, s49, 0
	s_add_i32 s22, s23, s56
	global_load_lds_dwordx4 v[214:215], off
	s_mov_b32 m0, s22
	s_nop 0
	global_load_lds_dwordx4 v130, s[48:49]
	s_add_i32 m0, s22, 0x2000
	s_nop 0
	global_load_lds_dwordx4 v134, s[48:49]
	v_lshl_add_u64 v[214:215], v[218:219], 0, s[34:35]
	s_mov_b32 m0, s63
	s_nop 0
	global_load_lds_dwordx4 v[214:215], off
	v_lshl_add_u64 v[214:215], v[220:221], 0, s[34:35]
	s_mov_b32 m0, s64
	s_nop 0
	global_load_lds_dwordx4 v[214:215], off
	s_waitcnt vmcnt(8)
	s_waitcnt lgkmcnt(0)
	s_barrier
	s_setprio 1
	s_waitcnt lgkmcnt(0)
	v_mfma_f32_16x16x32_bf16 v[60:63], v[144:147], v[182:185], v[60:63]
	v_mfma_f32_16x16x32_bf16 v[56:59], v[158:161], v[182:185], v[56:59]
	v_mfma_f32_16x16x32_bf16 v[44:47], v[144:147], v[190:193], v[44:47]
	v_mfma_f32_16x16x32_bf16 v[40:43], v[158:161], v[190:193], v[40:43]
	v_mfma_f32_16x16x32_bf16 v[28:31], v[144:147], v[198:201], v[28:31]
	v_mfma_f32_16x16x32_bf16 v[24:27], v[158:161], v[198:201], v[24:27]
	v_mfma_f32_16x16x32_bf16 v[12:15], v[144:147], v[206:209], v[12:15]
	v_mfma_f32_16x16x32_bf16 v[8:11], v[158:161], v[206:209], v[8:11]
	v_mfma_f32_16x16x32_bf16 v[60:63], v[154:157], v[186:189], v[60:63]
	v_mfma_f32_16x16x32_bf16 v[56:59], v[162:165], v[186:189], v[56:59]
	v_mfma_f32_16x16x32_bf16 v[44:47], v[154:157], v[194:197], v[44:47]
	v_mfma_f32_16x16x32_bf16 v[40:43], v[162:165], v[194:197], v[40:43]
	v_mfma_f32_16x16x32_bf16 v[28:31], v[154:157], v[202:205], v[28:31]
	v_mfma_f32_16x16x32_bf16 v[24:27], v[162:165], v[202:205], v[24:27]
	v_mfma_f32_16x16x32_bf16 v[12:15], v[154:157], v[210:213], v[12:15]
	v_mfma_f32_16x16x32_bf16 v[8:11], v[162:165], v[210:213], v[8:11]
	s_setprio 0
	s_setprio 1
	v_mfma_f32_16x16x32_bf16 v[52:55], v[166:169], v[182:185], v[52:55]
	v_mfma_f32_16x16x32_bf16 v[48:51], v[174:177], v[182:185], v[48:51]
	v_mfma_f32_16x16x32_bf16 v[36:39], v[166:169], v[190:193], v[36:39]
	v_mfma_f32_16x16x32_bf16 v[32:35], v[174:177], v[190:193], v[32:35]
	v_mfma_f32_16x16x32_bf16 v[20:23], v[166:169], v[198:201], v[20:23]
	v_mfma_f32_16x16x32_bf16 v[16:19], v[174:177], v[198:201], v[16:19]
	v_mfma_f32_16x16x32_bf16 v[4:7], v[166:169], v[206:209], v[4:7]
	v_mfma_f32_16x16x32_bf16 v[0:3], v[174:177], v[206:209], v[0:3]
	v_mfma_f32_16x16x32_bf16 v[52:55], v[170:173], v[186:189], v[52:55]
	v_mfma_f32_16x16x32_bf16 v[48:51], v[178:181], v[186:189], v[48:51]
	v_mfma_f32_16x16x32_bf16 v[36:39], v[170:173], v[194:197], v[36:39]
	v_mfma_f32_16x16x32_bf16 v[32:35], v[178:181], v[194:197], v[32:35]
	v_mfma_f32_16x16x32_bf16 v[20:23], v[170:173], v[202:205], v[20:23]
	v_mfma_f32_16x16x32_bf16 v[16:19], v[178:181], v[202:205], v[16:19]
	v_mfma_f32_16x16x32_bf16 v[4:7], v[170:173], v[210:213], v[4:7]
	v_mfma_f32_16x16x32_bf16 v[0:3], v[178:181], v[210:213], v[0:3]
	s_setprio 0
	s_barrier
	s_add_i32 s71, s71, 2
	s_add_u32 s68, s68, 0x100
	s_addc_u32 s69, s69, 0
	s_add_u32 s46, s46, 0x100
	s_addc_u32 s47, s47, 0
	s_cmp_gt_u32 s71, 13
	s_cbranch_scc0 .LBB0_733
	s_and_b64 vcc, exec, s[36:37]
	s_cbranch_vccz .LBB0_736
	s_barrier

.LBB0_849:
	ds_read_b128 v[146:149], v227
	ds_read_b128 v[150:153], v227 offset:1024
	ds_read_b128 v[154:157], v227 offset:2048
	ds_read_b128 v[158:161], v227 offset:3072
	ds_read_b128 v[162:165], v228
	ds_read_b128 v[166:169], v228 offset:1024
	ds_read_b128 v[170:173], v228 offset:2048
	ds_read_b128 v[174:177], v228 offset:3072
	s_add_u32 s22, s12, 0xfffc2080
	s_addc_u32 s23, s13, -1
	s_cmp_eq_u32 vcc_hi, 12
	s_cselect_b32 s65, s59, s23
	s_cselect_b32 s64, s58, s22
	s_cselect_b32 s63, s27, vcc_lo
	s_cselect_b32 s62, s57, s71
	s_add_i32 m0, s69, 0xc000
	ds_read_b128 v[178:181], v229
	ds_read_b128 v[182:185], v229 offset:1024
	ds_read_b128 v[186:189], v229 offset:2048
	ds_read_b128 v[190:193], v229 offset:3072
	ds_read_b128 v[194:197], v229 offset:4096
	ds_read_b128 v[198:201], v229 offset:5120
	ds_read_b128 v[202:205], v229 offset:6144
	ds_read_b128 v[206:209], v229 offset:7168
	global_load_lds_dwordx4 v138, s[12:13]
	s_add_i32 m0, s69, 0xe000
	s_nop 0
	global_load_lds_dwordx4 v136, s[12:13]
	s_waitcnt vmcnt(8)
	s_waitcnt lgkmcnt(0)
	s_barrier
	s_setprio 1
	s_waitcnt lgkmcnt(0)
	v_mfma_f32_16x16x32_bf16 v[124:127], v[146:149], v[178:181], v[124:127]
	v_mfma_f32_16x16x32_bf16 v[120:123], v[154:157], v[178:181], v[120:123]
	v_mfma_f32_16x16x32_bf16 v[116:119], v[146:149], v[186:189], v[116:119]
	v_mfma_f32_16x16x32_bf16 v[108:111], v[154:157], v[186:189], v[108:111]
	v_mfma_f32_16x16x32_bf16 v[100:103], v[146:149], v[194:197], v[100:103]
	v_mfma_f32_16x16x32_bf16 v[96:99], v[154:157], v[194:197], v[96:99]
	v_mfma_f32_16x16x32_bf16 v[84:87], v[146:149], v[202:205], v[84:87]
	v_mfma_f32_16x16x32_bf16 v[76:79], v[154:157], v[202:205], v[76:79]
	v_mfma_f32_16x16x32_bf16 v[124:127], v[150:153], v[182:185], v[124:127]
	v_mfma_f32_16x16x32_bf16 v[120:123], v[158:161], v[182:185], v[120:123]
	v_mfma_f32_16x16x32_bf16 v[116:119], v[150:153], v[190:193], v[116:119]
	v_mfma_f32_16x16x32_bf16 v[108:111], v[158:161], v[190:193], v[108:111]
	v_mfma_f32_16x16x32_bf16 v[100:103], v[150:153], v[198:201], v[100:103]
	v_mfma_f32_16x16x32_bf16 v[96:99], v[158:161], v[198:201], v[96:99]
	v_mfma_f32_16x16x32_bf16 v[84:87], v[150:153], v[206:209], v[84:87]
	v_mfma_f32_16x16x32_bf16 v[76:79], v[158:161], v[206:209], v[76:79]
	s_setprio 0
	s_setprio 1
	v_mfma_f32_16x16x32_bf16 v[112:115], v[162:165], v[178:181], v[112:115]
	v_mfma_f32_16x16x32_bf16 v[104:107], v[170:173], v[178:181], v[104:107]
	v_mfma_f32_16x16x32_bf16 v[92:95], v[162:165], v[186:189], v[92:95]
	v_mfma_f32_16x16x32_bf16 v[88:91], v[170:173], v[186:189], v[88:91]
	v_mfma_f32_16x16x32_bf16 v[80:83], v[162:165], v[194:197], v[80:83]
	v_mfma_f32_16x16x32_bf16 v[72:75], v[170:173], v[194:197], v[72:75]
	v_mfma_f32_16x16x32_bf16 v[68:71], v[162:165], v[202:205], v[68:71]
	v_mfma_f32_16x16x32_bf16 v[64:67], v[170:173], v[202:205], v[64:67]
	v_mfma_f32_16x16x32_bf16 v[112:115], v[166:169], v[182:185], v[112:115]
	v_mfma_f32_16x16x32_bf16 v[104:107], v[174:177], v[182:185], v[104:107]
	v_mfma_f32_16x16x32_bf16 v[92:95], v[166:169], v[190:193], v[92:95]
	v_mfma_f32_16x16x32_bf16 v[88:91], v[174:177], v[190:193], v[88:91]
	v_mfma_f32_16x16x32_bf16 v[80:83], v[166:169], v[198:201], v[80:83]
	v_mfma_f32_16x16x32_bf16 v[72:75], v[174:177], v[198:201], v[72:75]
	v_mfma_f32_16x16x32_bf16 v[68:71], v[166:169], v[206:209], v[68:71]
	v_mfma_f32_16x16x32_bf16 v[64:67], v[174:177], v[206:209], v[64:67]
	s_setprio 0
	s_barrier
	s_add_i32 s22, s91, s53
	v_lshl_add_u64 v[210:211], s[62:63], 0, v[130:131]
	s_mov_b32 m0, s22
	ds_read_b128 v[178:181], v229 offset:16384
	ds_read_b128 v[182:185], v229 offset:17408
	ds_read_b128 v[186:189], v229 offset:18432
	ds_read_b128 v[190:193], v229 offset:19456
	ds_read_b128 v[194:197], v229 offset:20480
	ds_read_b128 v[198:201], v229 offset:21504
	ds_read_b128 v[202:205], v229 offset:22528
	ds_read_b128 v[206:209], v229 offset:23552
	global_load_lds_dwordx4 v[210:211], off
	s_add_i32 m0, s22, 0x2000
	s_add_u32 s22, s62, 0x40000
	v_lshl_add_u64 v[212:213], s[62:63], 0, v[134:135]
	s_addc_u32 s23, s63, 0
	s_add_i32 s70, s92, s53
	global_load_lds_dwordx4 v[212:213], off
	s_mov_b32 m0, s70
	v_lshl_add_u64 v[216:217], s[64:65], 0, v[132:133]
	global_load_lds_dwordx4 v130, s[22:23]
	s_add_i32 m0, s70, 0x2000
	s_nop 0
	global_load_lds_dwordx4 v134, s[22:23]
	v_lshl_add_u64 v[214:215], s[64:65], 0, v[128:129]
	s_mov_b32 m0, s69
	s_nop 0
	global_load_lds_dwordx4 v[214:215], off
	s_mov_b32 m0, s82
	s_nop 0
	global_load_lds_dwordx4 v[216:217], off
	s_waitcnt vmcnt(8)
	s_waitcnt lgkmcnt(0)
	s_barrier
	s_setprio 1
	s_waitcnt lgkmcnt(0)
	v_mfma_f32_16x16x32_bf16 v[60:63], v[146:149], v[178:181], v[60:63]
	v_mfma_f32_16x16x32_bf16 v[56:59], v[154:157], v[178:181], v[56:59]
	v_mfma_f32_16x16x32_bf16 v[52:55], v[146:149], v[186:189], v[52:55]
	v_mfma_f32_16x16x32_bf16 v[44:47], v[154:157], v[186:189], v[44:47]
	v_mfma_f32_16x16x32_bf16 v[36:39], v[146:149], v[194:197], v[36:39]
	v_mfma_f32_16x16x32_bf16 v[32:35], v[154:157], v[194:197], v[32:35]
	v_mfma_f32_16x16x32_bf16 v[20:23], v[146:149], v[202:205], v[20:23]
	v_mfma_f32_16x16x32_bf16 v[12:15], v[154:157], v[202:205], v[12:15]
	v_mfma_f32_16x16x32_bf16 v[60:63], v[150:153], v[182:185], v[60:63]
	v_mfma_f32_16x16x32_bf16 v[56:59], v[158:161], v[182:185], v[56:59]
	v_mfma_f32_16x16x32_bf16 v[52:55], v[150:153], v[190:193], v[52:55]
	v_mfma_f32_16x16x32_bf16 v[44:47], v[158:161], v[190:193], v[44:47]
	v_mfma_f32_16x16x32_bf16 v[36:39], v[150:153], v[198:201], v[36:39]
	v_mfma_f32_16x16x32_bf16 v[32:35], v[158:161], v[198:201], v[32:35]
	v_mfma_f32_16x16x32_bf16 v[20:23], v[150:153], v[206:209], v[20:23]
	v_mfma_f32_16x16x32_bf16 v[12:15], v[158:161], v[206:209], v[12:15]
	s_setprio 0
	s_setprio 1
	v_mfma_f32_16x16x32_bf16 v[48:51], v[162:165], v[178:181], v[48:51]
	v_mfma_f32_16x16x32_bf16 v[40:43], v[170:173], v[178:181], v[40:43]
	v_mfma_f32_16x16x32_bf16 v[28:31], v[162:165], v[186:189], v[28:31]
	v_mfma_f32_16x16x32_bf16 v[24:27], v[170:173], v[186:189], v[24:27]
	v_mfma_f32_16x16x32_bf16 v[16:19], v[162:165], v[194:197], v[16:19]
	v_mfma_f32_16x16x32_bf16 v[8:11], v[170:173], v[194:197], v[8:11]
	v_mfma_f32_16x16x32_bf16 v[4:7], v[162:165], v[202:205], v[4:7]
	v_mfma_f32_16x16x32_bf16 v[0:3], v[170:173], v[202:205], v[0:3]
	v_mfma_f32_16x16x32_bf16 v[48:51], v[166:169], v[182:185], v[48:51]
	v_mfma_f32_16x16x32_bf16 v[40:43], v[174:177], v[182:185], v[40:43]
	v_mfma_f32_16x16x32_bf16 v[28:31], v[166:169], v[190:193], v[28:31]
	v_mfma_f32_16x16x32_bf16 v[24:27], v[174:177], v[190:193], v[24:27]
	v_mfma_f32_16x16x32_bf16 v[16:19], v[166:169], v[198:201], v[16:19]
	v_mfma_f32_16x16x32_bf16 v[8:11], v[174:177], v[198:201], v[8:11]
	v_mfma_f32_16x16x32_bf16 v[4:7], v[166:169], v[206:209], v[4:7]
	v_mfma_f32_16x16x32_bf16 v[0:3], v[174:177], v[206:209], v[0:3]
	s_setprio 0
	s_barrier
	s_add_i32 s70, 0, 0x18000
	s_add_i32 s81, 0, 0x1c000
	v_add_u32_e32 v158, s70, v226
	v_add_u32_e32 v174, s81, v226
	ds_read_b128 v[146:149], v158
	ds_read_b128 v[150:153], v158 offset:1024
	ds_read_b128 v[154:157], v158 offset:2048
	ds_read_b128 v[158:161], v158 offset:3072
	ds_read_b128 v[162:165], v174
	ds_read_b128 v[166:169], v174 offset:1024
	ds_read_b128 v[170:173], v174 offset:2048
	ds_read_b128 v[174:177], v174 offset:3072
	s_add_u32 s22, s64, 0x3e000
	s_addc_u32 s23, s65, 0
	s_mov_b32 m0, s83
	ds_read_b128 v[178:181], v229 offset:32768
	ds_read_b128 v[182:185], v229 offset:33792
	ds_read_b128 v[186:189], v229 offset:34816
	ds_read_b128 v[190:193], v229 offset:35840
	ds_read_b128 v[194:197], v229 offset:36864
	ds_read_b128 v[198:201], v229 offset:37888
	ds_read_b128 v[202:205], v229 offset:38912
	ds_read_b128 v[206:209], v229 offset:39936
	global_load_lds_dwordx4 v128, s[22:23]
	s_mov_b32 m0, s84
	s_nop 0
	global_load_lds_dwordx4 v132, s[22:23]
	s_waitcnt vmcnt(8)
	s_waitcnt lgkmcnt(0)
	s_barrier
	s_setprio 1
	s_waitcnt lgkmcnt(0)
	v_mfma_f32_16x16x32_bf16 v[124:127], v[146:149], v[178:181], v[124:127]
	v_mfma_f32_16x16x32_bf16 v[120:123], v[154:157], v[178:181], v[120:123]
	v_mfma_f32_16x16x32_bf16 v[116:119], v[146:149], v[186:189], v[116:119]
	v_mfma_f32_16x16x32_bf16 v[108:111], v[154:157], v[186:189], v[108:111]
	v_mfma_f32_16x16x32_bf16 v[100:103], v[146:149], v[194:197], v[100:103]
	v_mfma_f32_16x16x32_bf16 v[96:99], v[154:157], v[194:197], v[96:99]
	v_mfma_f32_16x16x32_bf16 v[84:87], v[146:149], v[202:205], v[84:87]
	v_mfma_f32_16x16x32_bf16 v[76:79], v[154:157], v[202:205], v[76:79]
	v_mfma_f32_16x16x32_bf16 v[124:127], v[150:153], v[182:185], v[124:127]
	v_mfma_f32_16x16x32_bf16 v[120:123], v[158:161], v[182:185], v[120:123]
	v_mfma_f32_16x16x32_bf16 v[116:119], v[150:153], v[190:193], v[116:119]
	v_mfma_f32_16x16x32_bf16 v[108:111], v[158:161], v[190:193], v[108:111]
	v_mfma_f32_16x16x32_bf16 v[100:103], v[150:153], v[198:201], v[100:103]
	v_mfma_f32_16x16x32_bf16 v[96:99], v[158:161], v[198:201], v[96:99]
	v_mfma_f32_16x16x32_bf16 v[84:87], v[150:153], v[206:209], v[84:87]
	v_mfma_f32_16x16x32_bf16 v[76:79], v[158:161], v[206:209], v[76:79]
	s_setprio 0
	s_setprio 1
	v_mfma_f32_16x16x32_bf16 v[112:115], v[162:165], v[178:181], v[112:115]
	v_mfma_f32_16x16x32_bf16 v[104:107], v[170:173], v[178:181], v[104:107]
	v_mfma_f32_16x16x32_bf16 v[92:95], v[162:165], v[186:189], v[92:95]
	v_mfma_f32_16x16x32_bf16 v[88:91], v[170:173], v[186:189], v[88:91]
	v_mfma_f32_16x16x32_bf16 v[80:83], v[162:165], v[194:197], v[80:83]
	v_mfma_f32_16x16x32_bf16 v[72:75], v[170:173], v[194:197], v[72:75]
	v_mfma_f32_16x16x32_bf16 v[68:71], v[162:165], v[202:205], v[68:71]
	v_mfma_f32_16x16x32_bf16 v[64:67], v[170:173], v[202:205], v[64:67]
	v_mfma_f32_16x16x32_bf16 v[112:115], v[166:169], v[182:185], v[112:115]
	v_mfma_f32_16x16x32_bf16 v[104:107], v[174:177], v[182:185], v[104:107]
	v_mfma_f32_16x16x32_bf16 v[92:95], v[166:169], v[190:193], v[92:95]
	v_mfma_f32_16x16x32_bf16 v[88:91], v[174:177], v[190:193], v[88:91]
	v_mfma_f32_16x16x32_bf16 v[80:83], v[166:169], v[198:201], v[80:83]
	v_mfma_f32_16x16x32_bf16 v[72:75], v[174:177], v[198:201], v[72:75]
	v_mfma_f32_16x16x32_bf16 v[68:71], v[166:169], v[206:209], v[68:71]
	v_mfma_f32_16x16x32_bf16 v[64:67], v[174:177], v[206:209], v[64:67]
	s_setprio 0
	s_barrier
	s_add_i32 s22, s70, s53
	v_lshl_add_u64 v[210:211], v[210:211], 0, s[48:49]
	s_mov_b32 m0, s22
	ds_read_b128 v[178:181], v229 offset:49152
	ds_read_b128 v[182:185], v229 offset:50176
	ds_read_b128 v[186:189], v229 offset:51200
	ds_read_b128 v[190:193], v229 offset:52224
	ds_read_b128 v[194:197], v229 offset:53248
	ds_read_b128 v[198:201], v229 offset:54272
	ds_read_b128 v[202:205], v229 offset:55296
	ds_read_b128 v[206:209], v229 offset:56320
	global_load_lds_dwordx4 v[210:211], off
	s_add_i32 m0, s22, 0x2000
	s_add_u32 s22, s62, 0x40080
	v_lshl_add_u64 v[210:211], v[212:213], 0, s[48:49]
	s_addc_u32 s23, s63, 0
	s_add_i32 s62, s81, s53
	global_load_lds_dwordx4 v[210:211], off
	s_mov_b32 m0, s62
	s_nop 0
	global_load_lds_dwordx4 v130, s[22:23]
	s_add_i32 m0, s62, 0x2000
	s_nop 0
	global_load_lds_dwordx4 v134, s[22:23]
	v_lshl_add_u64 v[210:211], v[214:215], 0, s[48:49]
	s_mov_b32 m0, s86
	s_nop 0
	global_load_lds_dwordx4 v[210:211], off
	v_lshl_add_u64 v[210:211], v[216:217], 0, s[48:49]
	s_mov_b32 m0, s87
	s_nop 0
	global_load_lds_dwordx4 v[210:211], off
	s_waitcnt vmcnt(8)
	s_waitcnt lgkmcnt(0)
	s_barrier
	s_setprio 1
	s_waitcnt lgkmcnt(0)
	v_mfma_f32_16x16x32_bf16 v[60:63], v[146:149], v[178:181], v[60:63]
	v_mfma_f32_16x16x32_bf16 v[56:59], v[154:157], v[178:181], v[56:59]
	v_mfma_f32_16x16x32_bf16 v[52:55], v[146:149], v[186:189], v[52:55]
	v_mfma_f32_16x16x32_bf16 v[44:47], v[154:157], v[186:189], v[44:47]
	v_mfma_f32_16x16x32_bf16 v[36:39], v[146:149], v[194:197], v[36:39]
	v_mfma_f32_16x16x32_bf16 v[32:35], v[154:157], v[194:197], v[32:35]
	v_mfma_f32_16x16x32_bf16 v[20:23], v[146:149], v[202:205], v[20:23]
	v_mfma_f32_16x16x32_bf16 v[12:15], v[154:157], v[202:205], v[12:15]
	v_mfma_f32_16x16x32_bf16 v[60:63], v[150:153], v[182:185], v[60:63]
	v_mfma_f32_16x16x32_bf16 v[56:59], v[158:161], v[182:185], v[56:59]
	v_mfma_f32_16x16x32_bf16 v[52:55], v[150:153], v[190:193], v[52:55]
	v_mfma_f32_16x16x32_bf16 v[44:47], v[158:161], v[190:193], v[44:47]
	v_mfma_f32_16x16x32_bf16 v[36:39], v[150:153], v[198:201], v[36:39]
	v_mfma_f32_16x16x32_bf16 v[32:35], v[158:161], v[198:201], v[32:35]
	v_mfma_f32_16x16x32_bf16 v[20:23], v[150:153], v[206:209], v[20:23]
	v_mfma_f32_16x16x32_bf16 v[12:15], v[158:161], v[206:209], v[12:15]
	s_setprio 0
	s_setprio 1
	v_mfma_f32_16x16x32_bf16 v[48:51], v[162:165], v[178:181], v[48:51]
	v_mfma_f32_16x16x32_bf16 v[40:43], v[170:173], v[178:181], v[40:43]
	v_mfma_f32_16x16x32_bf16 v[28:31], v[162:165], v[186:189], v[28:31]
	v_mfma_f32_16x16x32_bf16 v[24:27], v[170:173], v[186:189], v[24:27]
	v_mfma_f32_16x16x32_bf16 v[16:19], v[162:165], v[194:197], v[16:19]
	v_mfma_f32_16x16x32_bf16 v[8:11], v[170:173], v[194:197], v[8:11]
	v_mfma_f32_16x16x32_bf16 v[4:7], v[162:165], v[202:205], v[4:7]
	v_mfma_f32_16x16x32_bf16 v[0:3], v[170:173], v[202:205], v[0:3]
	v_mfma_f32_16x16x32_bf16 v[48:51], v[166:169], v[182:185], v[48:51]
	v_mfma_f32_16x16x32_bf16 v[40:43], v[174:177], v[182:185], v[40:43]
	v_mfma_f32_16x16x32_bf16 v[28:31], v[166:169], v[190:193], v[28:31]
	v_mfma_f32_16x16x32_bf16 v[24:27], v[174:177], v[190:193], v[24:27]
	v_mfma_f32_16x16x32_bf16 v[16:19], v[166:169], v[198:201], v[16:19]
	v_mfma_f32_16x16x32_bf16 v[8:11], v[174:177], v[198:201], v[8:11]
	v_mfma_f32_16x16x32_bf16 v[4:7], v[166:169], v[206:209], v[4:7]
	v_mfma_f32_16x16x32_bf16 v[0:3], v[174:177], v[206:209], v[0:3]
	s_setprio 0
	s_barrier
	s_add_i32 vcc_hi, vcc_hi, 2
	s_add_u32 s71, s71, 0x100
	s_addc_u32 vcc_lo, vcc_lo, 0
	s_add_u32 s12, s12, 0x100
	s_addc_u32 s13, s13, 0
	s_cmp_gt_u32 vcc_hi, 13
	s_cbranch_scc0 .LBB0_849
	s_and_b64 vcc, exec, s[50:51]
	s_cbranch_vccz .LBB0_852
	s_barrier

.LBB0_1059:
	ds_read_b128 v[144:147], v151
	ds_read_b128 v[154:157], v151 offset:1024
	ds_read_b128 v[158:161], v151 offset:2048
	ds_read_b128 v[162:165], v151 offset:3072
	ds_read_b128 v[166:169], v152
	ds_read_b128 v[170:173], v152 offset:1024
	ds_read_b128 v[174:177], v152 offset:2048
	ds_read_b128 v[178:181], v152 offset:3072
	s_add_u32 s46, s44, 0x100
	s_addc_u32 s47, s45, 0
	s_cmp_eq_u32 s71, 40
	s_cselect_b32 s51, s13, s47
	s_cselect_b32 s50, s12, s46
	s_cselect_b32 s49, s43, s27
	s_cselect_b32 s48, s42, s26
	s_add_i32 m0, s58, 0xc000
	ds_read_b128 v[182:185], v153
	ds_read_b128 v[186:189], v153 offset:1024
	ds_read_b128 v[190:193], v153 offset:2048
	ds_read_b128 v[194:197], v153 offset:3072
	ds_read_b128 v[198:201], v153 offset:4096
	ds_read_b128 v[202:205], v153 offset:5120
	ds_read_b128 v[206:209], v153 offset:6144
	ds_read_b128 v[210:213], v153 offset:7168
	global_load_lds_dwordx4 v138, s[44:45]
	s_add_i32 m0, s58, 0xe000
	s_nop 0
	global_load_lds_dwordx4 v136, s[44:45]
	s_waitcnt vmcnt(8)
	s_waitcnt lgkmcnt(0)
	s_barrier
	s_setprio 1
	s_waitcnt lgkmcnt(0)
	v_mfma_f32_16x16x32_bf16 v[124:127], v[144:147], v[182:185], v[124:127]
	v_mfma_f32_16x16x32_bf16 v[120:123], v[158:161], v[182:185], v[120:123]
	v_mfma_f32_16x16x32_bf16 v[108:111], v[144:147], v[190:193], v[108:111]
	v_mfma_f32_16x16x32_bf16 v[104:107], v[158:161], v[190:193], v[104:107]
	v_mfma_f32_16x16x32_bf16 v[92:95], v[144:147], v[198:201], v[92:95]
	v_mfma_f32_16x16x32_bf16 v[88:91], v[158:161], v[198:201], v[88:91]
	v_mfma_f32_16x16x32_bf16 v[76:79], v[144:147], v[206:209], v[76:79]
	v_mfma_f32_16x16x32_bf16 v[72:75], v[158:161], v[206:209], v[72:75]
	v_mfma_f32_16x16x32_bf16 v[124:127], v[154:157], v[186:189], v[124:127]
	v_mfma_f32_16x16x32_bf16 v[120:123], v[162:165], v[186:189], v[120:123]
	v_mfma_f32_16x16x32_bf16 v[108:111], v[154:157], v[194:197], v[108:111]
	v_mfma_f32_16x16x32_bf16 v[104:107], v[162:165], v[194:197], v[104:107]
	v_mfma_f32_16x16x32_bf16 v[92:95], v[154:157], v[202:205], v[92:95]
	v_mfma_f32_16x16x32_bf16 v[88:91], v[162:165], v[202:205], v[88:91]
	v_mfma_f32_16x16x32_bf16 v[76:79], v[154:157], v[210:213], v[76:79]
	v_mfma_f32_16x16x32_bf16 v[72:75], v[162:165], v[210:213], v[72:75]
	s_setprio 0
	s_setprio 1
	v_mfma_f32_16x16x32_bf16 v[116:119], v[166:169], v[182:185], v[116:119]
	v_mfma_f32_16x16x32_bf16 v[112:115], v[174:177], v[182:185], v[112:115]
	v_mfma_f32_16x16x32_bf16 v[100:103], v[166:169], v[190:193], v[100:103]
	v_mfma_f32_16x16x32_bf16 v[96:99], v[174:177], v[190:193], v[96:99]
	v_mfma_f32_16x16x32_bf16 v[84:87], v[166:169], v[198:201], v[84:87]
	v_mfma_f32_16x16x32_bf16 v[80:83], v[174:177], v[198:201], v[80:83]
	v_mfma_f32_16x16x32_bf16 v[68:71], v[166:169], v[206:209], v[68:71]
	v_mfma_f32_16x16x32_bf16 v[64:67], v[174:177], v[206:209], v[64:67]
	v_mfma_f32_16x16x32_bf16 v[116:119], v[170:173], v[186:189], v[116:119]
	v_mfma_f32_16x16x32_bf16 v[112:115], v[178:181], v[186:189], v[112:115]
	v_mfma_f32_16x16x32_bf16 v[100:103], v[170:173], v[194:197], v[100:103]
	v_mfma_f32_16x16x32_bf16 v[96:99], v[178:181], v[194:197], v[96:99]
	v_mfma_f32_16x16x32_bf16 v[84:87], v[170:173], v[202:205], v[84:87]
	v_mfma_f32_16x16x32_bf16 v[80:83], v[178:181], v[202:205], v[80:83]
	v_mfma_f32_16x16x32_bf16 v[68:71], v[170:173], v[210:213], v[68:71]
	v_mfma_f32_16x16x32_bf16 v[64:67], v[178:181], v[210:213], v[64:67]
	s_setprio 0
	s_barrier
	s_add_i32 s22, s67, s57
	v_lshl_add_u64 v[214:215], s[48:49], 0, v[130:131]
	s_mov_b32 m0, s22
	ds_read_b128 v[182:185], v153 offset:16384
	ds_read_b128 v[186:189], v153 offset:17408
	ds_read_b128 v[190:193], v153 offset:18432
	ds_read_b128 v[194:197], v153 offset:19456
	ds_read_b128 v[198:201], v153 offset:20480
	ds_read_b128 v[202:205], v153 offset:21504
	ds_read_b128 v[206:209], v153 offset:22528
	ds_read_b128 v[210:213], v153 offset:23552
	global_load_lds_dwordx4 v[214:215], off
	s_add_i32 m0, s22, 0x2000
	s_add_u32 s22, s48, 0xb0000
	v_lshl_add_u64 v[216:217], s[48:49], 0, v[134:135]
	s_addc_u32 s23, s49, 0
	s_add_i32 s44, s68, s57
	global_load_lds_dwordx4 v[216:217], off
	s_mov_b32 m0, s44
	v_lshl_add_u64 v[220:221], s[50:51], 0, v[132:133]
	global_load_lds_dwordx4 v130, s[22:23]
	s_add_i32 m0, s44, 0x2000
	s_nop 0
	global_load_lds_dwordx4 v134, s[22:23]
	v_lshl_add_u64 v[218:219], s[50:51], 0, v[128:129]
	s_mov_b32 m0, s58
	s_nop 0
	global_load_lds_dwordx4 v[218:219], off
	s_mov_b32 m0, s59
	s_nop 0
	global_load_lds_dwordx4 v[220:221], off
	s_waitcnt vmcnt(8)
	s_waitcnt lgkmcnt(0)
	s_barrier
	s_setprio 1
	s_waitcnt lgkmcnt(0)
	v_mfma_f32_16x16x32_bf16 v[60:63], v[144:147], v[182:185], v[60:63]
	v_mfma_f32_16x16x32_bf16 v[56:59], v[158:161], v[182:185], v[56:59]
	v_mfma_f32_16x16x32_bf16 v[44:47], v[144:147], v[190:193], v[44:47]
	v_mfma_f32_16x16x32_bf16 v[40:43], v[158:161], v[190:193], v[40:43]
	v_mfma_f32_16x16x32_bf16 v[28:31], v[144:147], v[198:201], v[28:31]
	v_mfma_f32_16x16x32_bf16 v[24:27], v[158:161], v[198:201], v[24:27]
	v_mfma_f32_16x16x32_bf16 v[12:15], v[144:147], v[206:209], v[12:15]
	v_mfma_f32_16x16x32_bf16 v[8:11], v[158:161], v[206:209], v[8:11]
	v_mfma_f32_16x16x32_bf16 v[60:63], v[154:157], v[186:189], v[60:63]
	v_mfma_f32_16x16x32_bf16 v[56:59], v[162:165], v[186:189], v[56:59]
	v_mfma_f32_16x16x32_bf16 v[44:47], v[154:157], v[194:197], v[44:47]
	v_mfma_f32_16x16x32_bf16 v[40:43], v[162:165], v[194:197], v[40:43]
	v_mfma_f32_16x16x32_bf16 v[28:31], v[154:157], v[202:205], v[28:31]
	v_mfma_f32_16x16x32_bf16 v[24:27], v[162:165], v[202:205], v[24:27]
	v_mfma_f32_16x16x32_bf16 v[12:15], v[154:157], v[210:213], v[12:15]
	v_mfma_f32_16x16x32_bf16 v[8:11], v[162:165], v[210:213], v[8:11]
	s_setprio 0
	s_setprio 1
	v_mfma_f32_16x16x32_bf16 v[52:55], v[166:169], v[182:185], v[52:55]
	v_mfma_f32_16x16x32_bf16 v[48:51], v[174:177], v[182:185], v[48:51]
	v_mfma_f32_16x16x32_bf16 v[36:39], v[166:169], v[190:193], v[36:39]
	v_mfma_f32_16x16x32_bf16 v[32:35], v[174:177], v[190:193], v[32:35]
	v_mfma_f32_16x16x32_bf16 v[20:23], v[166:169], v[198:201], v[20:23]
	v_mfma_f32_16x16x32_bf16 v[16:19], v[174:177], v[198:201], v[16:19]
	v_mfma_f32_16x16x32_bf16 v[4:7], v[166:169], v[206:209], v[4:7]
	v_mfma_f32_16x16x32_bf16 v[0:3], v[174:177], v[206:209], v[0:3]
	v_mfma_f32_16x16x32_bf16 v[52:55], v[170:173], v[186:189], v[52:55]
	v_mfma_f32_16x16x32_bf16 v[48:51], v[178:181], v[186:189], v[48:51]
	v_mfma_f32_16x16x32_bf16 v[36:39], v[170:173], v[194:197], v[36:39]
	v_mfma_f32_16x16x32_bf16 v[32:35], v[178:181], v[194:197], v[32:35]
	v_mfma_f32_16x16x32_bf16 v[20:23], v[170:173], v[202:205], v[20:23]
	v_mfma_f32_16x16x32_bf16 v[16:19], v[178:181], v[202:205], v[16:19]
	v_mfma_f32_16x16x32_bf16 v[4:7], v[170:173], v[210:213], v[4:7]
	v_mfma_f32_16x16x32_bf16 v[0:3], v[178:181], v[210:213], v[0:3]
	s_setprio 0
	s_barrier
	s_add_i32 s44, 0, 0x18000
	s_add_i32 s45, 0, 0x1c000
	v_add_u32_e32 v162, s44, v150
	v_add_u32_e32 v178, s45, v150
	ds_read_b128 v[144:147], v162
	ds_read_b128 v[154:157], v162 offset:1024
	ds_read_b128 v[158:161], v162 offset:2048
	ds_read_b128 v[162:165], v162 offset:3072
	ds_read_b128 v[166:169], v178
	ds_read_b128 v[170:173], v178 offset:1024
	ds_read_b128 v[174:177], v178 offset:2048
	ds_read_b128 v[178:181], v178 offset:3072
	s_add_u32 s22, s50, 0xb0000
	s_addc_u32 s23, s51, 0
	s_mov_b32 m0, s60
	ds_read_b128 v[182:185], v153 offset:32768
	ds_read_b128 v[186:189], v153 offset:33792
	ds_read_b128 v[190:193], v153 offset:34816
	ds_read_b128 v[194:197], v153 offset:35840
	ds_read_b128 v[198:201], v153 offset:36864
	ds_read_b128 v[202:205], v153 offset:37888
	ds_read_b128 v[206:209], v153 offset:38912
	ds_read_b128 v[210:213], v153 offset:39936
	global_load_lds_dwordx4 v128, s[22:23]
	s_mov_b32 m0, s61
	s_nop 0
	global_load_lds_dwordx4 v132, s[22:23]
	s_waitcnt vmcnt(8)
	s_waitcnt lgkmcnt(0)
	s_barrier
	s_setprio 1
	s_waitcnt lgkmcnt(0)
	v_mfma_f32_16x16x32_bf16 v[124:127], v[144:147], v[182:185], v[124:127]
	v_mfma_f32_16x16x32_bf16 v[120:123], v[158:161], v[182:185], v[120:123]
	v_mfma_f32_16x16x32_bf16 v[108:111], v[144:147], v[190:193], v[108:111]
	v_mfma_f32_16x16x32_bf16 v[104:107], v[158:161], v[190:193], v[104:107]
	v_mfma_f32_16x16x32_bf16 v[92:95], v[144:147], v[198:201], v[92:95]
	v_mfma_f32_16x16x32_bf16 v[88:91], v[158:161], v[198:201], v[88:91]
	v_mfma_f32_16x16x32_bf16 v[76:79], v[144:147], v[206:209], v[76:79]
	v_mfma_f32_16x16x32_bf16 v[72:75], v[158:161], v[206:209], v[72:75]
	v_mfma_f32_16x16x32_bf16 v[124:127], v[154:157], v[186:189], v[124:127]
	v_mfma_f32_16x16x32_bf16 v[120:123], v[162:165], v[186:189], v[120:123]
	v_mfma_f32_16x16x32_bf16 v[108:111], v[154:157], v[194:197], v[108:111]
	v_mfma_f32_16x16x32_bf16 v[104:107], v[162:165], v[194:197], v[104:107]
	v_mfma_f32_16x16x32_bf16 v[92:95], v[154:157], v[202:205], v[92:95]
	v_mfma_f32_16x16x32_bf16 v[88:91], v[162:165], v[202:205], v[88:91]
	v_mfma_f32_16x16x32_bf16 v[76:79], v[154:157], v[210:213], v[76:79]
	v_mfma_f32_16x16x32_bf16 v[72:75], v[162:165], v[210:213], v[72:75]
	s_setprio 0
	s_setprio 1
	v_mfma_f32_16x16x32_bf16 v[116:119], v[166:169], v[182:185], v[116:119]
	v_mfma_f32_16x16x32_bf16 v[112:115], v[174:177], v[182:185], v[112:115]
	v_mfma_f32_16x16x32_bf16 v[100:103], v[166:169], v[190:193], v[100:103]
	v_mfma_f32_16x16x32_bf16 v[96:99], v[174:177], v[190:193], v[96:99]
	v_mfma_f32_16x16x32_bf16 v[84:87], v[166:169], v[198:201], v[84:87]
	v_mfma_f32_16x16x32_bf16 v[80:83], v[174:177], v[198:201], v[80:83]
	v_mfma_f32_16x16x32_bf16 v[68:71], v[166:169], v[206:209], v[68:71]
	v_mfma_f32_16x16x32_bf16 v[64:67], v[174:177], v[206:209], v[64:67]
	v_mfma_f32_16x16x32_bf16 v[116:119], v[170:173], v[186:189], v[116:119]
	v_mfma_f32_16x16x32_bf16 v[112:115], v[178:181], v[186:189], v[112:115]
	v_mfma_f32_16x16x32_bf16 v[100:103], v[170:173], v[194:197], v[100:103]
	v_mfma_f32_16x16x32_bf16 v[96:99], v[178:181], v[194:197], v[96:99]
	v_mfma_f32_16x16x32_bf16 v[84:87], v[170:173], v[202:205], v[84:87]
	v_mfma_f32_16x16x32_bf16 v[80:83], v[178:181], v[202:205], v[80:83]
	v_mfma_f32_16x16x32_bf16 v[68:71], v[170:173], v[210:213], v[68:71]
	v_mfma_f32_16x16x32_bf16 v[64:67], v[178:181], v[210:213], v[64:67]
	s_setprio 0
	s_barrier
	s_add_i32 s22, s44, s57
	v_lshl_add_u64 v[214:215], v[214:215], 0, s[38:39]
	s_mov_b32 m0, s22
	ds_read_b128 v[182:185], v153 offset:49152
	ds_read_b128 v[186:189], v153 offset:50176
	ds_read_b128 v[190:193], v153 offset:51200
	ds_read_b128 v[194:197], v153 offset:52224
	ds_read_b128 v[198:201], v153 offset:53248
	ds_read_b128 v[202:205], v153 offset:54272
	ds_read_b128 v[206:209], v153 offset:55296
	ds_read_b128 v[210:213], v153 offset:56320
	global_load_lds_dwordx4 v[214:215], off
	s_add_i32 m0, s22, 0x2000
	s_add_u32 s22, s48, 0xb0080
	v_lshl_add_u64 v[214:215], v[216:217], 0, s[38:39]
	s_addc_u32 s23, s49, 0
	s_add_i32 s44, s45, s57
	global_load_lds_dwordx4 v[214:215], off
	s_mov_b32 m0, s44
	s_nop 0
	global_load_lds_dwordx4 v130, s[22:23]
	s_add_i32 m0, s44, 0x2000
	s_nop 0
	global_load_lds_dwordx4 v134, s[22:23]
	v_lshl_add_u64 v[214:215], v[218:219], 0, s[38:39]
	s_mov_b32 m0, s65
	s_nop 0
	global_load_lds_dwordx4 v[214:215], off
	v_lshl_add_u64 v[214:215], v[220:221], 0, s[38:39]
	s_mov_b32 m0, s66
	s_nop 0
	global_load_lds_dwordx4 v[214:215], off
	s_waitcnt vmcnt(8)
	s_waitcnt lgkmcnt(0)
	s_barrier
	s_setprio 1
	s_waitcnt lgkmcnt(0)
	v_mfma_f32_16x16x32_bf16 v[60:63], v[144:147], v[182:185], v[60:63]
	v_mfma_f32_16x16x32_bf16 v[56:59], v[158:161], v[182:185], v[56:59]
	v_mfma_f32_16x16x32_bf16 v[44:47], v[144:147], v[190:193], v[44:47]
	v_mfma_f32_16x16x32_bf16 v[40:43], v[158:161], v[190:193], v[40:43]
	v_mfma_f32_16x16x32_bf16 v[28:31], v[144:147], v[198:201], v[28:31]
	v_mfma_f32_16x16x32_bf16 v[24:27], v[158:161], v[198:201], v[24:27]
	v_mfma_f32_16x16x32_bf16 v[12:15], v[144:147], v[206:209], v[12:15]
	v_mfma_f32_16x16x32_bf16 v[8:11], v[158:161], v[206:209], v[8:11]
	v_mfma_f32_16x16x32_bf16 v[60:63], v[154:157], v[186:189], v[60:63]
	v_mfma_f32_16x16x32_bf16 v[56:59], v[162:165], v[186:189], v[56:59]
	v_mfma_f32_16x16x32_bf16 v[44:47], v[154:157], v[194:197], v[44:47]
	v_mfma_f32_16x16x32_bf16 v[40:43], v[162:165], v[194:197], v[40:43]
	v_mfma_f32_16x16x32_bf16 v[28:31], v[154:157], v[202:205], v[28:31]
	v_mfma_f32_16x16x32_bf16 v[24:27], v[162:165], v[202:205], v[24:27]
	v_mfma_f32_16x16x32_bf16 v[12:15], v[154:157], v[210:213], v[12:15]
	v_mfma_f32_16x16x32_bf16 v[8:11], v[162:165], v[210:213], v[8:11]
	s_setprio 0
	s_setprio 1
	v_mfma_f32_16x16x32_bf16 v[52:55], v[166:169], v[182:185], v[52:55]
	v_mfma_f32_16x16x32_bf16 v[48:51], v[174:177], v[182:185], v[48:51]
	v_mfma_f32_16x16x32_bf16 v[36:39], v[166:169], v[190:193], v[36:39]
	v_mfma_f32_16x16x32_bf16 v[32:35], v[174:177], v[190:193], v[32:35]
	v_mfma_f32_16x16x32_bf16 v[20:23], v[166:169], v[198:201], v[20:23]
	v_mfma_f32_16x16x32_bf16 v[16:19], v[174:177], v[198:201], v[16:19]
	v_mfma_f32_16x16x32_bf16 v[4:7], v[166:169], v[206:209], v[4:7]
	v_mfma_f32_16x16x32_bf16 v[0:3], v[174:177], v[206:209], v[0:3]
	v_mfma_f32_16x16x32_bf16 v[52:55], v[170:173], v[186:189], v[52:55]
	v_mfma_f32_16x16x32_bf16 v[48:51], v[178:181], v[186:189], v[48:51]
	v_mfma_f32_16x16x32_bf16 v[36:39], v[170:173], v[194:197], v[36:39]
	v_mfma_f32_16x16x32_bf16 v[32:35], v[178:181], v[194:197], v[32:35]
	v_mfma_f32_16x16x32_bf16 v[20:23], v[170:173], v[202:205], v[20:23]
	v_mfma_f32_16x16x32_bf16 v[16:19], v[178:181], v[202:205], v[16:19]
	v_mfma_f32_16x16x32_bf16 v[4:7], v[170:173], v[210:213], v[4:7]
	v_mfma_f32_16x16x32_bf16 v[0:3], v[178:181], v[210:213], v[0:3]
	s_setprio 0
	s_barrier
	s_add_i32 s71, s71, 2
	s_add_u32 s26, s26, 0x100
	s_addc_u32 s27, s27, 0
	s_cmp_gt_u32 s71, 41
	s_mov_b64 s[44:45], s[46:47]
	s_cbranch_scc0 .LBB0_1059
	s_and_b64 vcc, exec, s[40:41]
	s_cbranch_vccz .LBB0_1062
	s_barrier

.LBB0_1161:
	ds_read_b128 v[144:147], v155
	ds_read_b128 v[148:151], v155 offset:1024
	ds_read_b128 v[158:161], v155 offset:2048
	ds_read_b128 v[162:165], v155 offset:3072
	ds_read_b128 v[166:169], v156
	ds_read_b128 v[170:173], v156 offset:1024
	ds_read_b128 v[174:177], v156 offset:2048
	ds_read_b128 v[178:181], v156 offset:3072
	s_add_u32 s22, s58, 0xfffc0080
	s_addc_u32 s23, s59, -1
	s_cmp_eq_u32 s94, 12
	s_cselect_b32 s63, s13, s23
	s_cselect_b32 s62, s26, s22
	s_cselect_b32 s61, s27, s57
	s_cselect_b32 s60, s49, s51
	s_add_i32 m0, s71, 0xc000
	ds_read_b128 v[182:185], v157
	ds_read_b128 v[186:189], v157 offset:1024
	ds_read_b128 v[190:193], v157 offset:2048
	ds_read_b128 v[194:197], v157 offset:3072
	ds_read_b128 v[198:201], v157 offset:4096
	ds_read_b128 v[202:205], v157 offset:5120
	ds_read_b128 v[206:209], v157 offset:6144
	ds_read_b128 v[210:213], v157 offset:7168
	global_load_lds_dwordx4 v138, s[58:59]
	s_add_i32 m0, s71, 0xe000
	s_nop 0
	global_load_lds_dwordx4 v136, s[58:59]
	s_waitcnt vmcnt(8)
	s_waitcnt lgkmcnt(0)
	s_barrier
	s_setprio 1
	s_waitcnt lgkmcnt(0)
	v_mfma_f32_16x16x32_bf16 v[124:127], v[144:147], v[182:185], v[124:127]
	v_mfma_f32_16x16x32_bf16 v[120:123], v[158:161], v[182:185], v[120:123]
	v_mfma_f32_16x16x32_bf16 v[108:111], v[144:147], v[190:193], v[108:111]
	v_mfma_f32_16x16x32_bf16 v[104:107], v[158:161], v[190:193], v[104:107]
	v_mfma_f32_16x16x32_bf16 v[92:95], v[144:147], v[198:201], v[92:95]
	v_mfma_f32_16x16x32_bf16 v[88:91], v[158:161], v[198:201], v[88:91]
	v_mfma_f32_16x16x32_bf16 v[76:79], v[144:147], v[206:209], v[76:79]
	v_mfma_f32_16x16x32_bf16 v[72:75], v[158:161], v[206:209], v[72:75]
	v_mfma_f32_16x16x32_bf16 v[124:127], v[148:151], v[186:189], v[124:127]
	v_mfma_f32_16x16x32_bf16 v[120:123], v[162:165], v[186:189], v[120:123]
	v_mfma_f32_16x16x32_bf16 v[108:111], v[148:151], v[194:197], v[108:111]
	v_mfma_f32_16x16x32_bf16 v[104:107], v[162:165], v[194:197], v[104:107]
	v_mfma_f32_16x16x32_bf16 v[92:95], v[148:151], v[202:205], v[92:95]
	v_mfma_f32_16x16x32_bf16 v[88:91], v[162:165], v[202:205], v[88:91]
	v_mfma_f32_16x16x32_bf16 v[76:79], v[148:151], v[210:213], v[76:79]
	v_mfma_f32_16x16x32_bf16 v[72:75], v[162:165], v[210:213], v[72:75]
	s_setprio 0
	s_setprio 1
	v_mfma_f32_16x16x32_bf16 v[116:119], v[166:169], v[182:185], v[116:119]
	v_mfma_f32_16x16x32_bf16 v[112:115], v[174:177], v[182:185], v[112:115]
	v_mfma_f32_16x16x32_bf16 v[100:103], v[166:169], v[190:193], v[100:103]
	v_mfma_f32_16x16x32_bf16 v[96:99], v[174:177], v[190:193], v[96:99]
	v_mfma_f32_16x16x32_bf16 v[84:87], v[166:169], v[198:201], v[84:87]
	v_mfma_f32_16x16x32_bf16 v[80:83], v[174:177], v[198:201], v[80:83]
	v_mfma_f32_16x16x32_bf16 v[68:71], v[166:169], v[206:209], v[68:71]
	v_mfma_f32_16x16x32_bf16 v[64:67], v[174:177], v[206:209], v[64:67]
	v_mfma_f32_16x16x32_bf16 v[116:119], v[170:173], v[186:189], v[116:119]
	v_mfma_f32_16x16x32_bf16 v[112:115], v[178:181], v[186:189], v[112:115]
	v_mfma_f32_16x16x32_bf16 v[100:103], v[170:173], v[194:197], v[100:103]
	v_mfma_f32_16x16x32_bf16 v[96:99], v[178:181], v[194:197], v[96:99]
	v_mfma_f32_16x16x32_bf16 v[84:87], v[170:173], v[202:205], v[84:87]
	v_mfma_f32_16x16x32_bf16 v[80:83], v[178:181], v[202:205], v[80:83]
	v_mfma_f32_16x16x32_bf16 v[68:71], v[170:173], v[210:213], v[68:71]
	v_mfma_f32_16x16x32_bf16 v[64:67], v[178:181], v[210:213], v[64:67]
	s_setprio 0
	s_barrier
	s_add_i32 s22, s91, s65
	v_lshl_add_u64 v[214:215], s[60:61], 0, v[130:131]
	s_mov_b32 m0, s22
	ds_read_b128 v[182:185], v157 offset:16384
	ds_read_b128 v[186:189], v157 offset:17408
	ds_read_b128 v[190:193], v157 offset:18432
	ds_read_b128 v[194:197], v157 offset:19456
	ds_read_b128 v[198:201], v157 offset:20480
	ds_read_b128 v[202:205], v157 offset:21504
	ds_read_b128 v[206:209], v157 offset:22528
	ds_read_b128 v[210:213], v157 offset:23552
	global_load_lds_dwordx4 v[214:215], off
	s_add_i32 m0, s22, 0x2000
	s_add_u32 s22, s60, 0x40000
	v_lshl_add_u64 v[216:217], s[60:61], 0, v[134:135]
	s_addc_u32 s23, s61, 0
	s_add_i32 s70, s92, s65
	global_load_lds_dwordx4 v[216:217], off
	s_mov_b32 m0, s70
	v_lshl_add_u64 v[220:221], s[62:63], 0, v[132:133]
	global_load_lds_dwordx4 v130, s[22:23]
	s_add_i32 m0, s70, 0x2000
	s_nop 0
	global_load_lds_dwordx4 v134, s[22:23]
	v_lshl_add_u64 v[218:219], s[62:63], 0, v[128:129]
	s_mov_b32 m0, s71
	s_nop 0
	global_load_lds_dwordx4 v[218:219], off
	s_mov_b32 m0, s82
	s_nop 0
	global_load_lds_dwordx4 v[220:221], off
	s_waitcnt vmcnt(8)
	s_waitcnt lgkmcnt(0)
	s_barrier
	s_setprio 1
	s_waitcnt lgkmcnt(0)
	v_mfma_f32_16x16x32_bf16 v[60:63], v[144:147], v[182:185], v[60:63]
	v_mfma_f32_16x16x32_bf16 v[56:59], v[158:161], v[182:185], v[56:59]
	v_mfma_f32_16x16x32_bf16 v[44:47], v[144:147], v[190:193], v[44:47]
	v_mfma_f32_16x16x32_bf16 v[40:43], v[158:161], v[190:193], v[40:43]
	v_mfma_f32_16x16x32_bf16 v[28:31], v[144:147], v[198:201], v[28:31]
	v_mfma_f32_16x16x32_bf16 v[24:27], v[158:161], v[198:201], v[24:27]
	v_mfma_f32_16x16x32_bf16 v[12:15], v[144:147], v[206:209], v[12:15]
	v_mfma_f32_16x16x32_bf16 v[8:11], v[158:161], v[206:209], v[8:11]
	v_mfma_f32_16x16x32_bf16 v[60:63], v[148:151], v[186:189], v[60:63]
	v_mfma_f32_16x16x32_bf16 v[56:59], v[162:165], v[186:189], v[56:59]
	v_mfma_f32_16x16x32_bf16 v[44:47], v[148:151], v[194:197], v[44:47]
	v_mfma_f32_16x16x32_bf16 v[40:43], v[162:165], v[194:197], v[40:43]
	v_mfma_f32_16x16x32_bf16 v[28:31], v[148:151], v[202:205], v[28:31]
	v_mfma_f32_16x16x32_bf16 v[24:27], v[162:165], v[202:205], v[24:27]
	v_mfma_f32_16x16x32_bf16 v[12:15], v[148:151], v[210:213], v[12:15]
	v_mfma_f32_16x16x32_bf16 v[8:11], v[162:165], v[210:213], v[8:11]
	s_setprio 0
	s_setprio 1
	v_mfma_f32_16x16x32_bf16 v[52:55], v[166:169], v[182:185], v[52:55]
	v_mfma_f32_16x16x32_bf16 v[48:51], v[174:177], v[182:185], v[48:51]
	v_mfma_f32_16x16x32_bf16 v[36:39], v[166:169], v[190:193], v[36:39]
	v_mfma_f32_16x16x32_bf16 v[32:35], v[174:177], v[190:193], v[32:35]
	v_mfma_f32_16x16x32_bf16 v[20:23], v[166:169], v[198:201], v[20:23]
	v_mfma_f32_16x16x32_bf16 v[16:19], v[174:177], v[198:201], v[16:19]
	v_mfma_f32_16x16x32_bf16 v[4:7], v[166:169], v[206:209], v[4:7]
	v_mfma_f32_16x16x32_bf16 v[0:3], v[174:177], v[206:209], v[0:3]
	v_mfma_f32_16x16x32_bf16 v[52:55], v[170:173], v[186:189], v[52:55]
	v_mfma_f32_16x16x32_bf16 v[48:51], v[178:181], v[186:189], v[48:51]
	v_mfma_f32_16x16x32_bf16 v[36:39], v[170:173], v[194:197], v[36:39]
	v_mfma_f32_16x16x32_bf16 v[32:35], v[178:181], v[194:197], v[32:35]
	v_mfma_f32_16x16x32_bf16 v[20:23], v[170:173], v[202:205], v[20:23]
	v_mfma_f32_16x16x32_bf16 v[16:19], v[178:181], v[202:205], v[16:19]
	v_mfma_f32_16x16x32_bf16 v[4:7], v[170:173], v[210:213], v[4:7]
	v_mfma_f32_16x16x32_bf16 v[0:3], v[178:181], v[210:213], v[0:3]
	s_setprio 0
	s_barrier
	s_add_i32 s70, 0, 0x18000
	s_add_i32 s81, 0, 0x1c000
	v_add_u32_e32 v162, s70, v154
	v_add_u32_e32 v178, s81, v154
	ds_read_b128 v[144:147], v162
	ds_read_b128 v[148:151], v162 offset:1024
	ds_read_b128 v[158:161], v162 offset:2048
	ds_read_b128 v[162:165], v162 offset:3072
	ds_read_b128 v[166:169], v178
	ds_read_b128 v[170:173], v178 offset:1024
	ds_read_b128 v[174:177], v178 offset:2048
	ds_read_b128 v[178:181], v178 offset:3072
	s_add_u32 s22, s62, 0x40000
	s_addc_u32 s23, s63, 0
	s_mov_b32 m0, s83
	ds_read_b128 v[182:185], v157 offset:32768
	ds_read_b128 v[186:189], v157 offset:33792
	ds_read_b128 v[190:193], v157 offset:34816
	ds_read_b128 v[194:197], v157 offset:35840
	ds_read_b128 v[198:201], v157 offset:36864
	ds_read_b128 v[202:205], v157 offset:37888
	ds_read_b128 v[206:209], v157 offset:38912
	ds_read_b128 v[210:213], v157 offset:39936
	global_load_lds_dwordx4 v128, s[22:23]
	s_mov_b32 m0, s84
	s_nop 0
	global_load_lds_dwordx4 v132, s[22:23]
	s_waitcnt vmcnt(8)
	s_waitcnt lgkmcnt(0)
	s_barrier
	s_setprio 1
	s_waitcnt lgkmcnt(0)
	v_mfma_f32_16x16x32_bf16 v[124:127], v[144:147], v[182:185], v[124:127]
	v_mfma_f32_16x16x32_bf16 v[120:123], v[158:161], v[182:185], v[120:123]
	v_mfma_f32_16x16x32_bf16 v[108:111], v[144:147], v[190:193], v[108:111]
	v_mfma_f32_16x16x32_bf16 v[104:107], v[158:161], v[190:193], v[104:107]
	v_mfma_f32_16x16x32_bf16 v[92:95], v[144:147], v[198:201], v[92:95]
	v_mfma_f32_16x16x32_bf16 v[88:91], v[158:161], v[198:201], v[88:91]
	v_mfma_f32_16x16x32_bf16 v[76:79], v[144:147], v[206:209], v[76:79]
	v_mfma_f32_16x16x32_bf16 v[72:75], v[158:161], v[206:209], v[72:75]
	v_mfma_f32_16x16x32_bf16 v[124:127], v[148:151], v[186:189], v[124:127]
	v_mfma_f32_16x16x32_bf16 v[120:123], v[162:165], v[186:189], v[120:123]
	v_mfma_f32_16x16x32_bf16 v[108:111], v[148:151], v[194:197], v[108:111]
	v_mfma_f32_16x16x32_bf16 v[104:107], v[162:165], v[194:197], v[104:107]
	v_mfma_f32_16x16x32_bf16 v[92:95], v[148:151], v[202:205], v[92:95]
	v_mfma_f32_16x16x32_bf16 v[88:91], v[162:165], v[202:205], v[88:91]
	v_mfma_f32_16x16x32_bf16 v[76:79], v[148:151], v[210:213], v[76:79]
	v_mfma_f32_16x16x32_bf16 v[72:75], v[162:165], v[210:213], v[72:75]
	s_setprio 0
	s_setprio 1
	v_mfma_f32_16x16x32_bf16 v[116:119], v[166:169], v[182:185], v[116:119]
	v_mfma_f32_16x16x32_bf16 v[112:115], v[174:177], v[182:185], v[112:115]
	v_mfma_f32_16x16x32_bf16 v[100:103], v[166:169], v[190:193], v[100:103]
	v_mfma_f32_16x16x32_bf16 v[96:99], v[174:177], v[190:193], v[96:99]
	v_mfma_f32_16x16x32_bf16 v[84:87], v[166:169], v[198:201], v[84:87]
	v_mfma_f32_16x16x32_bf16 v[80:83], v[174:177], v[198:201], v[80:83]
	v_mfma_f32_16x16x32_bf16 v[68:71], v[166:169], v[206:209], v[68:71]
	v_mfma_f32_16x16x32_bf16 v[64:67], v[174:177], v[206:209], v[64:67]
	v_mfma_f32_16x16x32_bf16 v[116:119], v[170:173], v[186:189], v[116:119]
	v_mfma_f32_16x16x32_bf16 v[112:115], v[178:181], v[186:189], v[112:115]
	v_mfma_f32_16x16x32_bf16 v[100:103], v[170:173], v[194:197], v[100:103]
	v_mfma_f32_16x16x32_bf16 v[96:99], v[178:181], v[194:197], v[96:99]
	v_mfma_f32_16x16x32_bf16 v[84:87], v[170:173], v[202:205], v[84:87]
	v_mfma_f32_16x16x32_bf16 v[80:83], v[178:181], v[202:205], v[80:83]
	v_mfma_f32_16x16x32_bf16 v[68:71], v[170:173], v[210:213], v[68:71]
	v_mfma_f32_16x16x32_bf16 v[64:67], v[178:181], v[210:213], v[64:67]
	s_setprio 0
	s_barrier
	s_add_i32 s22, s70, s65
	v_lshl_add_u64 v[214:215], v[214:215], 0, s[44:45]
	s_mov_b32 m0, s22
	ds_read_b128 v[182:185], v157 offset:49152
	ds_read_b128 v[186:189], v157 offset:50176
	ds_read_b128 v[190:193], v157 offset:51200
	ds_read_b128 v[194:197], v157 offset:52224
	ds_read_b128 v[198:201], v157 offset:53248
	ds_read_b128 v[202:205], v157 offset:54272
	ds_read_b128 v[206:209], v157 offset:55296
	ds_read_b128 v[210:213], v157 offset:56320
	global_load_lds_dwordx4 v[214:215], off
	s_add_i32 m0, s22, 0x2000
	s_add_u32 s22, s60, 0x40080
	v_lshl_add_u64 v[214:215], v[216:217], 0, s[44:45]
	s_addc_u32 s23, s61, 0
	s_add_i32 s60, s81, s65
	global_load_lds_dwordx4 v[214:215], off
	s_mov_b32 m0, s60
	s_nop 0
	global_load_lds_dwordx4 v130, s[22:23]
	s_add_i32 m0, s60, 0x2000
	s_nop 0
	global_load_lds_dwordx4 v134, s[22:23]
	v_lshl_add_u64 v[214:215], v[218:219], 0, s[44:45]
	s_mov_b32 m0, s88
	s_nop 0
	global_load_lds_dwordx4 v[214:215], off
	v_lshl_add_u64 v[214:215], v[220:221], 0, s[44:45]
	s_mov_b32 m0, s89
	s_nop 0
	global_load_lds_dwordx4 v[214:215], off
	s_waitcnt vmcnt(8)
	s_waitcnt lgkmcnt(0)
	s_barrier
	s_setprio 1
	s_waitcnt lgkmcnt(0)
	v_mfma_f32_16x16x32_bf16 v[60:63], v[144:147], v[182:185], v[60:63]
	v_mfma_f32_16x16x32_bf16 v[56:59], v[158:161], v[182:185], v[56:59]
	v_mfma_f32_16x16x32_bf16 v[44:47], v[144:147], v[190:193], v[44:47]
	v_mfma_f32_16x16x32_bf16 v[40:43], v[158:161], v[190:193], v[40:43]
	v_mfma_f32_16x16x32_bf16 v[28:31], v[144:147], v[198:201], v[28:31]
	v_mfma_f32_16x16x32_bf16 v[24:27], v[158:161], v[198:201], v[24:27]
	v_mfma_f32_16x16x32_bf16 v[12:15], v[144:147], v[206:209], v[12:15]
	v_mfma_f32_16x16x32_bf16 v[8:11], v[158:161], v[206:209], v[8:11]
	v_mfma_f32_16x16x32_bf16 v[60:63], v[148:151], v[186:189], v[60:63]
	v_mfma_f32_16x16x32_bf16 v[56:59], v[162:165], v[186:189], v[56:59]
	v_mfma_f32_16x16x32_bf16 v[44:47], v[148:151], v[194:197], v[44:47]
	v_mfma_f32_16x16x32_bf16 v[40:43], v[162:165], v[194:197], v[40:43]
	v_mfma_f32_16x16x32_bf16 v[28:31], v[148:151], v[202:205], v[28:31]
	v_mfma_f32_16x16x32_bf16 v[24:27], v[162:165], v[202:205], v[24:27]
	v_mfma_f32_16x16x32_bf16 v[12:15], v[148:151], v[210:213], v[12:15]
	v_mfma_f32_16x16x32_bf16 v[8:11], v[162:165], v[210:213], v[8:11]
	s_setprio 0
	s_setprio 1
	v_mfma_f32_16x16x32_bf16 v[52:55], v[166:169], v[182:185], v[52:55]
	v_mfma_f32_16x16x32_bf16 v[48:51], v[174:177], v[182:185], v[48:51]
	v_mfma_f32_16x16x32_bf16 v[36:39], v[166:169], v[190:193], v[36:39]
	v_mfma_f32_16x16x32_bf16 v[32:35], v[174:177], v[190:193], v[32:35]
	v_mfma_f32_16x16x32_bf16 v[20:23], v[166:169], v[198:201], v[20:23]
	v_mfma_f32_16x16x32_bf16 v[16:19], v[174:177], v[198:201], v[16:19]
	v_mfma_f32_16x16x32_bf16 v[4:7], v[166:169], v[206:209], v[4:7]
	v_mfma_f32_16x16x32_bf16 v[0:3], v[174:177], v[206:209], v[0:3]
	v_mfma_f32_16x16x32_bf16 v[52:55], v[170:173], v[186:189], v[52:55]
	v_mfma_f32_16x16x32_bf16 v[48:51], v[178:181], v[186:189], v[48:51]
	v_mfma_f32_16x16x32_bf16 v[36:39], v[170:173], v[194:197], v[36:39]
	v_mfma_f32_16x16x32_bf16 v[32:35], v[178:181], v[194:197], v[32:35]
	v_mfma_f32_16x16x32_bf16 v[20:23], v[170:173], v[202:205], v[20:23]
	v_mfma_f32_16x16x32_bf16 v[16:19], v[178:181], v[202:205], v[16:19]
	v_mfma_f32_16x16x32_bf16 v[4:7], v[170:173], v[210:213], v[4:7]
	v_mfma_f32_16x16x32_bf16 v[0:3], v[178:181], v[210:213], v[0:3]
	s_setprio 0
	s_barrier
	s_add_i32 s94, s94, 2
	s_add_u32 s51, s51, 0x100
	s_addc_u32 s57, s57, 0
	s_add_u32 s58, s58, 0x100
	s_addc_u32 s59, s59, 0
	s_cmp_gt_u32 s94, 13
	s_cbranch_scc0 .LBB0_1161
	s_and_b64 vcc, exec, s[46:47]
	s_cbranch_vccz .LBB0_1164
	s_barrier

.LBB0_1603:
	ds_read_b128 v[144:147], v151
	ds_read_b128 v[154:157], v151 offset:1024
	ds_read_b128 v[158:161], v151 offset:2048
	ds_read_b128 v[162:165], v151 offset:3072
	ds_read_b128 v[166:169], v152
	ds_read_b128 v[170:173], v152 offset:1024
	ds_read_b128 v[174:177], v152 offset:2048
	ds_read_b128 v[178:181], v152 offset:3072
	s_add_u32 s48, s46, 0xfffc0080
	s_addc_u32 s49, s47, -1
	s_cmp_eq_u32 s71, 12
	s_cselect_b32 s51, s26, s49
	s_cselect_b32 s50, s27, s48
	s_cselect_b32 s49, s39, s69
	s_cselect_b32 s48, s41, s68
	s_add_i32 m0, s15, 0xc000
	ds_read_b128 v[182:185], v153
	ds_read_b128 v[186:189], v153 offset:1024
	ds_read_b128 v[190:193], v153 offset:2048
	ds_read_b128 v[194:197], v153 offset:3072
	ds_read_b128 v[198:201], v153 offset:4096
	ds_read_b128 v[202:205], v153 offset:5120
	ds_read_b128 v[206:209], v153 offset:6144
	ds_read_b128 v[210:213], v153 offset:7168
	global_load_lds_dwordx4 v138, s[46:47]
	s_add_i32 m0, s15, 0xe000
	s_nop 0
	global_load_lds_dwordx4 v136, s[46:47]
	s_waitcnt vmcnt(8)
	s_waitcnt lgkmcnt(0)
	s_barrier
	s_setprio 1
	s_waitcnt lgkmcnt(0)
	v_mfma_f32_16x16x32_bf16 v[124:127], v[144:147], v[182:185], v[124:127]
	v_mfma_f32_16x16x32_bf16 v[120:123], v[158:161], v[182:185], v[120:123]
	v_mfma_f32_16x16x32_bf16 v[108:111], v[144:147], v[190:193], v[108:111]
	v_mfma_f32_16x16x32_bf16 v[104:107], v[158:161], v[190:193], v[104:107]
	v_mfma_f32_16x16x32_bf16 v[92:95], v[144:147], v[198:201], v[92:95]
	v_mfma_f32_16x16x32_bf16 v[88:91], v[158:161], v[198:201], v[88:91]
	v_mfma_f32_16x16x32_bf16 v[76:79], v[144:147], v[206:209], v[76:79]
	v_mfma_f32_16x16x32_bf16 v[72:75], v[158:161], v[206:209], v[72:75]
	v_mfma_f32_16x16x32_bf16 v[124:127], v[154:157], v[186:189], v[124:127]
	v_mfma_f32_16x16x32_bf16 v[120:123], v[162:165], v[186:189], v[120:123]
	v_mfma_f32_16x16x32_bf16 v[108:111], v[154:157], v[194:197], v[108:111]
	v_mfma_f32_16x16x32_bf16 v[104:107], v[162:165], v[194:197], v[104:107]
	v_mfma_f32_16x16x32_bf16 v[92:95], v[154:157], v[202:205], v[92:95]
	v_mfma_f32_16x16x32_bf16 v[88:91], v[162:165], v[202:205], v[88:91]
	v_mfma_f32_16x16x32_bf16 v[76:79], v[154:157], v[210:213], v[76:79]
	v_mfma_f32_16x16x32_bf16 v[72:75], v[162:165], v[210:213], v[72:75]
	s_setprio 0
	s_setprio 1
	v_mfma_f32_16x16x32_bf16 v[116:119], v[166:169], v[182:185], v[116:119]
	v_mfma_f32_16x16x32_bf16 v[112:115], v[174:177], v[182:185], v[112:115]
	v_mfma_f32_16x16x32_bf16 v[100:103], v[166:169], v[190:193], v[100:103]
	v_mfma_f32_16x16x32_bf16 v[96:99], v[174:177], v[190:193], v[96:99]
	v_mfma_f32_16x16x32_bf16 v[84:87], v[166:169], v[198:201], v[84:87]
	v_mfma_f32_16x16x32_bf16 v[80:83], v[174:177], v[198:201], v[80:83]
	v_mfma_f32_16x16x32_bf16 v[68:71], v[166:169], v[206:209], v[68:71]
	v_mfma_f32_16x16x32_bf16 v[64:67], v[174:177], v[206:209], v[64:67]
	v_mfma_f32_16x16x32_bf16 v[116:119], v[170:173], v[186:189], v[116:119]
	v_mfma_f32_16x16x32_bf16 v[112:115], v[178:181], v[186:189], v[112:115]
	v_mfma_f32_16x16x32_bf16 v[100:103], v[170:173], v[194:197], v[100:103]
	v_mfma_f32_16x16x32_bf16 v[96:99], v[178:181], v[194:197], v[96:99]
	v_mfma_f32_16x16x32_bf16 v[84:87], v[170:173], v[202:205], v[84:87]
	v_mfma_f32_16x16x32_bf16 v[80:83], v[178:181], v[202:205], v[80:83]
	v_mfma_f32_16x16x32_bf16 v[68:71], v[170:173], v[210:213], v[68:71]
	v_mfma_f32_16x16x32_bf16 v[64:67], v[178:181], v[210:213], v[64:67]
	s_setprio 0
	s_barrier
	s_add_i32 s70, s65, s56
	v_lshl_add_u64 v[214:215], s[48:49], 0, v[130:131]
	s_mov_b32 m0, s70
	ds_read_b128 v[182:185], v153 offset:16384
	ds_read_b128 v[186:189], v153 offset:17408
	ds_read_b128 v[190:193], v153 offset:18432
	ds_read_b128 v[194:197], v153 offset:19456
	ds_read_b128 v[198:201], v153 offset:20480
	ds_read_b128 v[202:205], v153 offset:21504
	ds_read_b128 v[206:209], v153 offset:22528
	ds_read_b128 v[210:213], v153 offset:23552
	global_load_lds_dwordx4 v[214:215], off
	s_add_i32 m0, s70, 0x2000
	s_add_u32 s78, s48, 0x40000
	v_lshl_add_u64 v[216:217], s[48:49], 0, v[134:135]
	s_addc_u32 s79, s49, 0
	s_add_i32 s70, s66, s56
	global_load_lds_dwordx4 v[216:217], off
	s_mov_b32 m0, s70
	v_lshl_add_u64 v[220:221], s[50:51], 0, v[132:133]
	global_load_lds_dwordx4 v130, s[78:79]
	s_add_i32 m0, s70, 0x2000
	s_nop 0
	global_load_lds_dwordx4 v134, s[78:79]
	v_lshl_add_u64 v[218:219], s[50:51], 0, v[128:129]
	s_mov_b32 m0, s15
	s_nop 0
	global_load_lds_dwordx4 v[218:219], off
	s_mov_b32 m0, s57
	s_nop 0
	global_load_lds_dwordx4 v[220:221], off
	s_waitcnt vmcnt(8)
	s_waitcnt lgkmcnt(0)
	s_barrier
	s_setprio 1
	s_waitcnt lgkmcnt(0)
	v_mfma_f32_16x16x32_bf16 v[60:63], v[144:147], v[182:185], v[60:63]
	v_mfma_f32_16x16x32_bf16 v[56:59], v[158:161], v[182:185], v[56:59]
	v_mfma_f32_16x16x32_bf16 v[44:47], v[144:147], v[190:193], v[44:47]
	v_mfma_f32_16x16x32_bf16 v[40:43], v[158:161], v[190:193], v[40:43]
	v_mfma_f32_16x16x32_bf16 v[28:31], v[144:147], v[198:201], v[28:31]
	v_mfma_f32_16x16x32_bf16 v[24:27], v[158:161], v[198:201], v[24:27]
	v_mfma_f32_16x16x32_bf16 v[12:15], v[144:147], v[206:209], v[12:15]
	v_mfma_f32_16x16x32_bf16 v[8:11], v[158:161], v[206:209], v[8:11]
	v_mfma_f32_16x16x32_bf16 v[60:63], v[154:157], v[186:189], v[60:63]
	v_mfma_f32_16x16x32_bf16 v[56:59], v[162:165], v[186:189], v[56:59]
	v_mfma_f32_16x16x32_bf16 v[44:47], v[154:157], v[194:197], v[44:47]
	v_mfma_f32_16x16x32_bf16 v[40:43], v[162:165], v[194:197], v[40:43]
	v_mfma_f32_16x16x32_bf16 v[28:31], v[154:157], v[202:205], v[28:31]
	v_mfma_f32_16x16x32_bf16 v[24:27], v[162:165], v[202:205], v[24:27]
	v_mfma_f32_16x16x32_bf16 v[12:15], v[154:157], v[210:213], v[12:15]
	v_mfma_f32_16x16x32_bf16 v[8:11], v[162:165], v[210:213], v[8:11]
	s_setprio 0
	s_setprio 1
	v_mfma_f32_16x16x32_bf16 v[52:55], v[166:169], v[182:185], v[52:55]
	v_mfma_f32_16x16x32_bf16 v[48:51], v[174:177], v[182:185], v[48:51]
	v_mfma_f32_16x16x32_bf16 v[36:39], v[166:169], v[190:193], v[36:39]
	v_mfma_f32_16x16x32_bf16 v[32:35], v[174:177], v[190:193], v[32:35]
	v_mfma_f32_16x16x32_bf16 v[20:23], v[166:169], v[198:201], v[20:23]
	v_mfma_f32_16x16x32_bf16 v[16:19], v[174:177], v[198:201], v[16:19]
	v_mfma_f32_16x16x32_bf16 v[4:7], v[166:169], v[206:209], v[4:7]
	v_mfma_f32_16x16x32_bf16 v[0:3], v[174:177], v[206:209], v[0:3]
	v_mfma_f32_16x16x32_bf16 v[52:55], v[170:173], v[186:189], v[52:55]
	v_mfma_f32_16x16x32_bf16 v[48:51], v[178:181], v[186:189], v[48:51]
	v_mfma_f32_16x16x32_bf16 v[36:39], v[170:173], v[194:197], v[36:39]
	v_mfma_f32_16x16x32_bf16 v[32:35], v[178:181], v[194:197], v[32:35]
	v_mfma_f32_16x16x32_bf16 v[20:23], v[170:173], v[202:205], v[20:23]
	v_mfma_f32_16x16x32_bf16 v[16:19], v[178:181], v[202:205], v[16:19]
	v_mfma_f32_16x16x32_bf16 v[4:7], v[170:173], v[210:213], v[4:7]
	v_mfma_f32_16x16x32_bf16 v[0:3], v[178:181], v[210:213], v[0:3]
	s_setprio 0
	s_barrier
	s_add_i32 s70, 0, 0x18000
	s_add_i32 s77, 0, 0x1c000
	v_add_u32_e32 v162, s70, v150
	v_add_u32_e32 v178, s77, v150
	ds_read_b128 v[144:147], v162
	ds_read_b128 v[154:157], v162 offset:1024
	ds_read_b128 v[158:161], v162 offset:2048
	ds_read_b128 v[162:165], v162 offset:3072
	ds_read_b128 v[166:169], v178
	ds_read_b128 v[170:173], v178 offset:1024
	ds_read_b128 v[174:177], v178 offset:2048
	ds_read_b128 v[178:181], v178 offset:3072
	s_add_u32 s50, s50, 0x40000
	s_addc_u32 s51, s51, 0
	s_mov_b32 m0, s58
	ds_read_b128 v[182:185], v153 offset:32768
	ds_read_b128 v[186:189], v153 offset:33792
	ds_read_b128 v[190:193], v153 offset:34816
	ds_read_b128 v[194:197], v153 offset:35840
	ds_read_b128 v[198:201], v153 offset:36864
	ds_read_b128 v[202:205], v153 offset:37888
	ds_read_b128 v[206:209], v153 offset:38912
	ds_read_b128 v[210:213], v153 offset:39936
	global_load_lds_dwordx4 v128, s[50:51]
	s_mov_b32 m0, s59
	s_nop 0
	global_load_lds_dwordx4 v132, s[50:51]
	s_waitcnt vmcnt(8)
	s_waitcnt lgkmcnt(0)
	s_barrier
	s_setprio 1
	s_waitcnt lgkmcnt(0)
	v_mfma_f32_16x16x32_bf16 v[124:127], v[144:147], v[182:185], v[124:127]
	v_mfma_f32_16x16x32_bf16 v[120:123], v[158:161], v[182:185], v[120:123]
	v_mfma_f32_16x16x32_bf16 v[108:111], v[144:147], v[190:193], v[108:111]
	v_mfma_f32_16x16x32_bf16 v[104:107], v[158:161], v[190:193], v[104:107]
	v_mfma_f32_16x16x32_bf16 v[92:95], v[144:147], v[198:201], v[92:95]
	v_mfma_f32_16x16x32_bf16 v[88:91], v[158:161], v[198:201], v[88:91]
	v_mfma_f32_16x16x32_bf16 v[76:79], v[144:147], v[206:209], v[76:79]
	v_mfma_f32_16x16x32_bf16 v[72:75], v[158:161], v[206:209], v[72:75]
	v_mfma_f32_16x16x32_bf16 v[124:127], v[154:157], v[186:189], v[124:127]
	v_mfma_f32_16x16x32_bf16 v[120:123], v[162:165], v[186:189], v[120:123]
	v_mfma_f32_16x16x32_bf16 v[108:111], v[154:157], v[194:197], v[108:111]
	v_mfma_f32_16x16x32_bf16 v[104:107], v[162:165], v[194:197], v[104:107]
	v_mfma_f32_16x16x32_bf16 v[92:95], v[154:157], v[202:205], v[92:95]
	v_mfma_f32_16x16x32_bf16 v[88:91], v[162:165], v[202:205], v[88:91]
	v_mfma_f32_16x16x32_bf16 v[76:79], v[154:157], v[210:213], v[76:79]
	v_mfma_f32_16x16x32_bf16 v[72:75], v[162:165], v[210:213], v[72:75]
	s_setprio 0
	s_setprio 1
	v_mfma_f32_16x16x32_bf16 v[116:119], v[166:169], v[182:185], v[116:119]
	v_mfma_f32_16x16x32_bf16 v[112:115], v[174:177], v[182:185], v[112:115]
	v_mfma_f32_16x16x32_bf16 v[100:103], v[166:169], v[190:193], v[100:103]
	v_mfma_f32_16x16x32_bf16 v[96:99], v[174:177], v[190:193], v[96:99]
	v_mfma_f32_16x16x32_bf16 v[84:87], v[166:169], v[198:201], v[84:87]
	v_mfma_f32_16x16x32_bf16 v[80:83], v[174:177], v[198:201], v[80:83]
	v_mfma_f32_16x16x32_bf16 v[68:71], v[166:169], v[206:209], v[68:71]
	v_mfma_f32_16x16x32_bf16 v[64:67], v[174:177], v[206:209], v[64:67]
	v_mfma_f32_16x16x32_bf16 v[116:119], v[170:173], v[186:189], v[116:119]
	v_mfma_f32_16x16x32_bf16 v[112:115], v[178:181], v[186:189], v[112:115]
	v_mfma_f32_16x16x32_bf16 v[100:103], v[170:173], v[194:197], v[100:103]
	v_mfma_f32_16x16x32_bf16 v[96:99], v[178:181], v[194:197], v[96:99]
	v_mfma_f32_16x16x32_bf16 v[84:87], v[170:173], v[202:205], v[84:87]
	v_mfma_f32_16x16x32_bf16 v[80:83], v[178:181], v[202:205], v[80:83]
	v_mfma_f32_16x16x32_bf16 v[68:71], v[170:173], v[210:213], v[68:71]
	v_mfma_f32_16x16x32_bf16 v[64:67], v[178:181], v[210:213], v[64:67]
	s_setprio 0
	s_barrier
	s_add_i32 s50, s70, s56
	v_lshl_add_u64 v[214:215], v[214:215], 0, s[22:23]
	s_mov_b32 m0, s50
	ds_read_b128 v[182:185], v153 offset:49152
	ds_read_b128 v[186:189], v153 offset:50176
	ds_read_b128 v[190:193], v153 offset:51200
	ds_read_b128 v[194:197], v153 offset:52224
	ds_read_b128 v[198:201], v153 offset:53248
	ds_read_b128 v[202:205], v153 offset:54272
	ds_read_b128 v[206:209], v153 offset:55296
	ds_read_b128 v[210:213], v153 offset:56320
	global_load_lds_dwordx4 v[214:215], off
	s_add_i32 m0, s50, 0x2000
	s_add_u32 s48, s48, 0x40080
	v_lshl_add_u64 v[214:215], v[216:217], 0, s[22:23]
	s_addc_u32 s49, s49, 0
	s_add_i32 s50, s77, s56
	global_load_lds_dwordx4 v[214:215], off
	s_mov_b32 m0, s50
	s_nop 0
	global_load_lds_dwordx4 v130, s[48:49]
	s_add_i32 m0, s50, 0x2000
	s_nop 0
	global_load_lds_dwordx4 v134, s[48:49]
	v_lshl_add_u64 v[214:215], v[218:219], 0, s[22:23]
	s_mov_b32 m0, s63
	s_nop 0
	global_load_lds_dwordx4 v[214:215], off
	v_lshl_add_u64 v[214:215], v[220:221], 0, s[22:23]
	s_mov_b32 m0, s64
	s_nop 0
	global_load_lds_dwordx4 v[214:215], off
	s_waitcnt vmcnt(8)
	s_waitcnt lgkmcnt(0)
	s_barrier
	s_setprio 1
	s_waitcnt lgkmcnt(0)
	v_mfma_f32_16x16x32_bf16 v[60:63], v[144:147], v[182:185], v[60:63]
	v_mfma_f32_16x16x32_bf16 v[56:59], v[158:161], v[182:185], v[56:59]
	v_mfma_f32_16x16x32_bf16 v[44:47], v[144:147], v[190:193], v[44:47]
	v_mfma_f32_16x16x32_bf16 v[40:43], v[158:161], v[190:193], v[40:43]
	v_mfma_f32_16x16x32_bf16 v[28:31], v[144:147], v[198:201], v[28:31]
	v_mfma_f32_16x16x32_bf16 v[24:27], v[158:161], v[198:201], v[24:27]
	v_mfma_f32_16x16x32_bf16 v[12:15], v[144:147], v[206:209], v[12:15]
	v_mfma_f32_16x16x32_bf16 v[8:11], v[158:161], v[206:209], v[8:11]
	v_mfma_f32_16x16x32_bf16 v[60:63], v[154:157], v[186:189], v[60:63]
	v_mfma_f32_16x16x32_bf16 v[56:59], v[162:165], v[186:189], v[56:59]
	v_mfma_f32_16x16x32_bf16 v[44:47], v[154:157], v[194:197], v[44:47]
	v_mfma_f32_16x16x32_bf16 v[40:43], v[162:165], v[194:197], v[40:43]
	v_mfma_f32_16x16x32_bf16 v[28:31], v[154:157], v[202:205], v[28:31]
	v_mfma_f32_16x16x32_bf16 v[24:27], v[162:165], v[202:205], v[24:27]
	v_mfma_f32_16x16x32_bf16 v[12:15], v[154:157], v[210:213], v[12:15]
	v_mfma_f32_16x16x32_bf16 v[8:11], v[162:165], v[210:213], v[8:11]
	s_setprio 0
	s_setprio 1
	v_mfma_f32_16x16x32_bf16 v[52:55], v[166:169], v[182:185], v[52:55]
	v_mfma_f32_16x16x32_bf16 v[48:51], v[174:177], v[182:185], v[48:51]
	v_mfma_f32_16x16x32_bf16 v[36:39], v[166:169], v[190:193], v[36:39]
	v_mfma_f32_16x16x32_bf16 v[32:35], v[174:177], v[190:193], v[32:35]
	v_mfma_f32_16x16x32_bf16 v[20:23], v[166:169], v[198:201], v[20:23]
	v_mfma_f32_16x16x32_bf16 v[16:19], v[174:177], v[198:201], v[16:19]
	v_mfma_f32_16x16x32_bf16 v[4:7], v[166:169], v[206:209], v[4:7]
	v_mfma_f32_16x16x32_bf16 v[0:3], v[174:177], v[206:209], v[0:3]
	v_mfma_f32_16x16x32_bf16 v[52:55], v[170:173], v[186:189], v[52:55]
	v_mfma_f32_16x16x32_bf16 v[48:51], v[178:181], v[186:189], v[48:51]
	v_mfma_f32_16x16x32_bf16 v[36:39], v[170:173], v[194:197], v[36:39]
	v_mfma_f32_16x16x32_bf16 v[32:35], v[178:181], v[194:197], v[32:35]
	v_mfma_f32_16x16x32_bf16 v[20:23], v[170:173], v[202:205], v[20:23]
	v_mfma_f32_16x16x32_bf16 v[16:19], v[178:181], v[202:205], v[16:19]
	v_mfma_f32_16x16x32_bf16 v[4:7], v[170:173], v[210:213], v[4:7]
	v_mfma_f32_16x16x32_bf16 v[0:3], v[178:181], v[210:213], v[0:3]
	s_setprio 0
	s_barrier
	s_add_i32 s71, s71, 2
	s_add_u32 s68, s68, 0x100
	s_addc_u32 s69, s69, 0
	s_add_u32 s46, s46, 0x100
	s_addc_u32 s47, s47, 0
	s_cmp_gt_u32 s71, 13
	s_cbranch_scc0 .LBB0_1603
	s_and_b64 vcc, exec, s[36:37]
	s_cbranch_vccz .LBB0_1606
	s_barrier

.LBB0_1719:
	ds_read_b128 v[146:149], v226
	ds_read_b128 v[150:153], v226 offset:1024
	ds_read_b128 v[154:157], v226 offset:2048
	ds_read_b128 v[158:161], v226 offset:3072
	ds_read_b128 v[162:165], v227
	ds_read_b128 v[166:169], v227 offset:1024
	ds_read_b128 v[170:173], v227 offset:2048
	ds_read_b128 v[174:177], v227 offset:3072
	s_add_u32 s52, s10, 0xfffc2080
	s_addc_u32 s53, s11, -1
	s_cmp_eq_u32 s82, 12
	s_cselect_b32 s55, s49, s53
	s_cselect_b32 s54, s48, s52
	s_cselect_b32 s53, s27, s81
	s_cselect_b32 s52, s47, s71
	s_add_i32 m0, s59, 0xc000
	ds_read_b128 v[178:181], v228
	ds_read_b128 v[182:185], v228 offset:1024
	ds_read_b128 v[186:189], v228 offset:2048
	ds_read_b128 v[190:193], v228 offset:3072
	ds_read_b128 v[194:197], v228 offset:4096
	ds_read_b128 v[198:201], v228 offset:5120
	ds_read_b128 v[202:205], v228 offset:6144
	ds_read_b128 v[206:209], v228 offset:7168
	global_load_lds_dwordx4 v138, s[10:11]
	s_add_i32 m0, s59, 0xe000
	s_nop 0
	global_load_lds_dwordx4 v136, s[10:11]
	s_waitcnt vmcnt(8)
	s_waitcnt lgkmcnt(0)
	s_barrier
	s_setprio 1
	s_waitcnt lgkmcnt(0)
	v_mfma_f32_16x16x32_bf16 v[124:127], v[146:149], v[178:181], v[124:127]
	v_mfma_f32_16x16x32_bf16 v[120:123], v[154:157], v[178:181], v[120:123]
	v_mfma_f32_16x16x32_bf16 v[116:119], v[146:149], v[186:189], v[116:119]
	v_mfma_f32_16x16x32_bf16 v[108:111], v[154:157], v[186:189], v[108:111]
	v_mfma_f32_16x16x32_bf16 v[100:103], v[146:149], v[194:197], v[100:103]
	v_mfma_f32_16x16x32_bf16 v[96:99], v[154:157], v[194:197], v[96:99]
	v_mfma_f32_16x16x32_bf16 v[84:87], v[146:149], v[202:205], v[84:87]
	v_mfma_f32_16x16x32_bf16 v[76:79], v[154:157], v[202:205], v[76:79]
	v_mfma_f32_16x16x32_bf16 v[124:127], v[150:153], v[182:185], v[124:127]
	v_mfma_f32_16x16x32_bf16 v[120:123], v[158:161], v[182:185], v[120:123]
	v_mfma_f32_16x16x32_bf16 v[116:119], v[150:153], v[190:193], v[116:119]
	v_mfma_f32_16x16x32_bf16 v[108:111], v[158:161], v[190:193], v[108:111]
	v_mfma_f32_16x16x32_bf16 v[100:103], v[150:153], v[198:201], v[100:103]
	v_mfma_f32_16x16x32_bf16 v[96:99], v[158:161], v[198:201], v[96:99]
	v_mfma_f32_16x16x32_bf16 v[84:87], v[150:153], v[206:209], v[84:87]
	v_mfma_f32_16x16x32_bf16 v[76:79], v[158:161], v[206:209], v[76:79]
	s_setprio 0
	s_setprio 1
	v_mfma_f32_16x16x32_bf16 v[112:115], v[162:165], v[178:181], v[112:115]
	v_mfma_f32_16x16x32_bf16 v[104:107], v[170:173], v[178:181], v[104:107]
	v_mfma_f32_16x16x32_bf16 v[92:95], v[162:165], v[186:189], v[92:95]
	v_mfma_f32_16x16x32_bf16 v[88:91], v[170:173], v[186:189], v[88:91]
	v_mfma_f32_16x16x32_bf16 v[80:83], v[162:165], v[194:197], v[80:83]
	v_mfma_f32_16x16x32_bf16 v[72:75], v[170:173], v[194:197], v[72:75]
	v_mfma_f32_16x16x32_bf16 v[68:71], v[162:165], v[202:205], v[68:71]
	v_mfma_f32_16x16x32_bf16 v[64:67], v[170:173], v[202:205], v[64:67]
	v_mfma_f32_16x16x32_bf16 v[112:115], v[166:169], v[182:185], v[112:115]
	v_mfma_f32_16x16x32_bf16 v[104:107], v[174:177], v[182:185], v[104:107]
	v_mfma_f32_16x16x32_bf16 v[92:95], v[166:169], v[190:193], v[92:95]
	v_mfma_f32_16x16x32_bf16 v[88:91], v[174:177], v[190:193], v[88:91]
	v_mfma_f32_16x16x32_bf16 v[80:83], v[166:169], v[198:201], v[80:83]
	v_mfma_f32_16x16x32_bf16 v[72:75], v[174:177], v[198:201], v[72:75]
	v_mfma_f32_16x16x32_bf16 v[68:71], v[166:169], v[206:209], v[68:71]
	v_mfma_f32_16x16x32_bf16 v[64:67], v[174:177], v[206:209], v[64:67]
	s_setprio 0
	s_barrier
	s_add_i32 s70, s69, s43
	v_lshl_add_u64 v[210:211], s[52:53], 0, v[130:131]
	s_mov_b32 m0, s70
	ds_read_b128 v[178:181], v228 offset:16384
	ds_read_b128 v[182:185], v228 offset:17408
	ds_read_b128 v[186:189], v228 offset:18432
	ds_read_b128 v[190:193], v228 offset:19456
	ds_read_b128 v[194:197], v228 offset:20480
	ds_read_b128 v[198:201], v228 offset:21504
	ds_read_b128 v[202:205], v228 offset:22528
	ds_read_b128 v[206:209], v228 offset:23552
	global_load_lds_dwordx4 v[210:211], off
	s_add_i32 m0, s70, 0x2000
	s_add_u32 s84, s52, 0x40000
	v_lshl_add_u64 v[212:213], s[52:53], 0, v[134:135]
	s_addc_u32 s85, s53, 0
	s_add_i32 s70, s75, s43
	global_load_lds_dwordx4 v[212:213], off
	s_mov_b32 m0, s70
	v_lshl_add_u64 v[216:217], s[54:55], 0, v[132:133]
	global_load_lds_dwordx4 v130, s[84:85]
	s_add_i32 m0, s70, 0x2000
	s_nop 0
	global_load_lds_dwordx4 v134, s[84:85]
	v_lshl_add_u64 v[214:215], s[54:55], 0, v[128:129]
	s_mov_b32 m0, s59
	s_nop 0
	global_load_lds_dwordx4 v[214:215], off
	s_mov_b32 m0, s60
	s_nop 0
	global_load_lds_dwordx4 v[216:217], off
	s_waitcnt vmcnt(8)
	s_waitcnt lgkmcnt(0)
	s_barrier
	s_setprio 1
	s_waitcnt lgkmcnt(0)
	v_mfma_f32_16x16x32_bf16 v[60:63], v[146:149], v[178:181], v[60:63]
	v_mfma_f32_16x16x32_bf16 v[56:59], v[154:157], v[178:181], v[56:59]
	v_mfma_f32_16x16x32_bf16 v[52:55], v[146:149], v[186:189], v[52:55]
	v_mfma_f32_16x16x32_bf16 v[44:47], v[154:157], v[186:189], v[44:47]
	v_mfma_f32_16x16x32_bf16 v[36:39], v[146:149], v[194:197], v[36:39]
	v_mfma_f32_16x16x32_bf16 v[32:35], v[154:157], v[194:197], v[32:35]
	v_mfma_f32_16x16x32_bf16 v[20:23], v[146:149], v[202:205], v[20:23]
	v_mfma_f32_16x16x32_bf16 v[12:15], v[154:157], v[202:205], v[12:15]
	v_mfma_f32_16x16x32_bf16 v[60:63], v[150:153], v[182:185], v[60:63]
	v_mfma_f32_16x16x32_bf16 v[56:59], v[158:161], v[182:185], v[56:59]
	v_mfma_f32_16x16x32_bf16 v[52:55], v[150:153], v[190:193], v[52:55]
	v_mfma_f32_16x16x32_bf16 v[44:47], v[158:161], v[190:193], v[44:47]
	v_mfma_f32_16x16x32_bf16 v[36:39], v[150:153], v[198:201], v[36:39]
	v_mfma_f32_16x16x32_bf16 v[32:35], v[158:161], v[198:201], v[32:35]
	v_mfma_f32_16x16x32_bf16 v[20:23], v[150:153], v[206:209], v[20:23]
	v_mfma_f32_16x16x32_bf16 v[12:15], v[158:161], v[206:209], v[12:15]
	s_setprio 0
	s_setprio 1
	v_mfma_f32_16x16x32_bf16 v[48:51], v[162:165], v[178:181], v[48:51]
	v_mfma_f32_16x16x32_bf16 v[40:43], v[170:173], v[178:181], v[40:43]
	v_mfma_f32_16x16x32_bf16 v[28:31], v[162:165], v[186:189], v[28:31]
	v_mfma_f32_16x16x32_bf16 v[24:27], v[170:173], v[186:189], v[24:27]
	v_mfma_f32_16x16x32_bf16 v[16:19], v[162:165], v[194:197], v[16:19]
	v_mfma_f32_16x16x32_bf16 v[8:11], v[170:173], v[194:197], v[8:11]
	v_mfma_f32_16x16x32_bf16 v[4:7], v[162:165], v[202:205], v[4:7]
	v_mfma_f32_16x16x32_bf16 v[0:3], v[170:173], v[202:205], v[0:3]
	v_mfma_f32_16x16x32_bf16 v[48:51], v[166:169], v[182:185], v[48:51]
	v_mfma_f32_16x16x32_bf16 v[40:43], v[174:177], v[182:185], v[40:43]
	v_mfma_f32_16x16x32_bf16 v[28:31], v[166:169], v[190:193], v[28:31]
	v_mfma_f32_16x16x32_bf16 v[24:27], v[174:177], v[190:193], v[24:27]
	v_mfma_f32_16x16x32_bf16 v[16:19], v[166:169], v[198:201], v[16:19]
	v_mfma_f32_16x16x32_bf16 v[8:11], v[174:177], v[198:201], v[8:11]
	v_mfma_f32_16x16x32_bf16 v[4:7], v[166:169], v[206:209], v[4:7]
	v_mfma_f32_16x16x32_bf16 v[0:3], v[174:177], v[206:209], v[0:3]
	s_setprio 0
	s_barrier
	s_add_i32 s70, 0, 0x18000
	s_add_i32 s83, 0, 0x1c000
	v_add_u32_e32 v158, s70, v225
	v_add_u32_e32 v174, s83, v225
	ds_read_b128 v[146:149], v158
	ds_read_b128 v[150:153], v158 offset:1024
	ds_read_b128 v[154:157], v158 offset:2048
	ds_read_b128 v[158:161], v158 offset:3072
	ds_read_b128 v[162:165], v174
	ds_read_b128 v[166:169], v174 offset:1024
	ds_read_b128 v[170:173], v174 offset:2048
	ds_read_b128 v[174:177], v174 offset:3072
	s_add_u32 s54, s54, 0x3e000
	s_addc_u32 s55, s55, 0
	s_mov_b32 m0, s61
	ds_read_b128 v[178:181], v228 offset:32768
	ds_read_b128 v[182:185], v228 offset:33792
	ds_read_b128 v[186:189], v228 offset:34816
	ds_read_b128 v[190:193], v228 offset:35840
	ds_read_b128 v[194:197], v228 offset:36864
	ds_read_b128 v[198:201], v228 offset:37888
	ds_read_b128 v[202:205], v228 offset:38912
	ds_read_b128 v[206:209], v228 offset:39936
	global_load_lds_dwordx4 v128, s[54:55]
	s_mov_b32 m0, s62
	s_nop 0
	global_load_lds_dwordx4 v132, s[54:55]
	s_waitcnt vmcnt(8)
	s_waitcnt lgkmcnt(0)
	s_barrier
	s_setprio 1
	s_waitcnt lgkmcnt(0)
	v_mfma_f32_16x16x32_bf16 v[124:127], v[146:149], v[178:181], v[124:127]
	v_mfma_f32_16x16x32_bf16 v[120:123], v[154:157], v[178:181], v[120:123]
	v_mfma_f32_16x16x32_bf16 v[116:119], v[146:149], v[186:189], v[116:119]
	v_mfma_f32_16x16x32_bf16 v[108:111], v[154:157], v[186:189], v[108:111]
	v_mfma_f32_16x16x32_bf16 v[100:103], v[146:149], v[194:197], v[100:103]
	v_mfma_f32_16x16x32_bf16 v[96:99], v[154:157], v[194:197], v[96:99]
	v_mfma_f32_16x16x32_bf16 v[84:87], v[146:149], v[202:205], v[84:87]
	v_mfma_f32_16x16x32_bf16 v[76:79], v[154:157], v[202:205], v[76:79]
	v_mfma_f32_16x16x32_bf16 v[124:127], v[150:153], v[182:185], v[124:127]
	v_mfma_f32_16x16x32_bf16 v[120:123], v[158:161], v[182:185], v[120:123]
	v_mfma_f32_16x16x32_bf16 v[116:119], v[150:153], v[190:193], v[116:119]
	v_mfma_f32_16x16x32_bf16 v[108:111], v[158:161], v[190:193], v[108:111]
	v_mfma_f32_16x16x32_bf16 v[100:103], v[150:153], v[198:201], v[100:103]
	v_mfma_f32_16x16x32_bf16 v[96:99], v[158:161], v[198:201], v[96:99]
	v_mfma_f32_16x16x32_bf16 v[84:87], v[150:153], v[206:209], v[84:87]
	v_mfma_f32_16x16x32_bf16 v[76:79], v[158:161], v[206:209], v[76:79]
	s_setprio 0
	s_setprio 1
	v_mfma_f32_16x16x32_bf16 v[112:115], v[162:165], v[178:181], v[112:115]
	v_mfma_f32_16x16x32_bf16 v[104:107], v[170:173], v[178:181], v[104:107]
	v_mfma_f32_16x16x32_bf16 v[92:95], v[162:165], v[186:189], v[92:95]
	v_mfma_f32_16x16x32_bf16 v[88:91], v[170:173], v[186:189], v[88:91]
	v_mfma_f32_16x16x32_bf16 v[80:83], v[162:165], v[194:197], v[80:83]
	v_mfma_f32_16x16x32_bf16 v[72:75], v[170:173], v[194:197], v[72:75]
	v_mfma_f32_16x16x32_bf16 v[68:71], v[162:165], v[202:205], v[68:71]
	v_mfma_f32_16x16x32_bf16 v[64:67], v[170:173], v[202:205], v[64:67]
	v_mfma_f32_16x16x32_bf16 v[112:115], v[166:169], v[182:185], v[112:115]
	v_mfma_f32_16x16x32_bf16 v[104:107], v[174:177], v[182:185], v[104:107]
	v_mfma_f32_16x16x32_bf16 v[92:95], v[166:169], v[190:193], v[92:95]
	v_mfma_f32_16x16x32_bf16 v[88:91], v[174:177], v[190:193], v[88:91]
	v_mfma_f32_16x16x32_bf16 v[80:83], v[166:169], v[198:201], v[80:83]
	v_mfma_f32_16x16x32_bf16 v[72:75], v[174:177], v[198:201], v[72:75]
	v_mfma_f32_16x16x32_bf16 v[68:71], v[166:169], v[206:209], v[68:71]
	v_mfma_f32_16x16x32_bf16 v[64:67], v[174:177], v[206:209], v[64:67]
	s_setprio 0
	s_barrier
	s_add_i32 s54, s70, s43
	v_lshl_add_u64 v[210:211], v[210:211], 0, s[36:37]
	s_mov_b32 m0, s54
	ds_read_b128 v[178:181], v228 offset:49152
	ds_read_b128 v[182:185], v228 offset:50176
	ds_read_b128 v[186:189], v228 offset:51200
	ds_read_b128 v[190:193], v228 offset:52224
	ds_read_b128 v[194:197], v228 offset:53248
	ds_read_b128 v[198:201], v228 offset:54272
	ds_read_b128 v[202:205], v228 offset:55296
	ds_read_b128 v[206:209], v228 offset:56320
	global_load_lds_dwordx4 v[210:211], off
	s_add_i32 m0, s54, 0x2000
	s_add_u32 s52, s52, 0x40080
	v_lshl_add_u64 v[210:211], v[212:213], 0, s[36:37]
	s_addc_u32 s53, s53, 0
	s_add_i32 s54, s83, s43
	global_load_lds_dwordx4 v[210:211], off
	s_mov_b32 m0, s54
	s_nop 0
	global_load_lds_dwordx4 v130, s[52:53]
	s_add_i32 m0, s54, 0x2000
	s_nop 0
	global_load_lds_dwordx4 v134, s[52:53]
	v_lshl_add_u64 v[210:211], v[214:215], 0, s[36:37]
	s_mov_b32 m0, s64
	s_nop 0
	global_load_lds_dwordx4 v[210:211], off
	v_lshl_add_u64 v[210:211], v[216:217], 0, s[36:37]
	s_mov_b32 m0, s65
	s_nop 0
	global_load_lds_dwordx4 v[210:211], off
	s_waitcnt vmcnt(8)
	s_waitcnt lgkmcnt(0)
	s_barrier
	s_setprio 1
	s_waitcnt lgkmcnt(0)
	v_mfma_f32_16x16x32_bf16 v[60:63], v[146:149], v[178:181], v[60:63]
	v_mfma_f32_16x16x32_bf16 v[56:59], v[154:157], v[178:181], v[56:59]
	v_mfma_f32_16x16x32_bf16 v[52:55], v[146:149], v[186:189], v[52:55]
	v_mfma_f32_16x16x32_bf16 v[44:47], v[154:157], v[186:189], v[44:47]
	v_mfma_f32_16x16x32_bf16 v[36:39], v[146:149], v[194:197], v[36:39]
	v_mfma_f32_16x16x32_bf16 v[32:35], v[154:157], v[194:197], v[32:35]
	v_mfma_f32_16x16x32_bf16 v[20:23], v[146:149], v[202:205], v[20:23]
	v_mfma_f32_16x16x32_bf16 v[12:15], v[154:157], v[202:205], v[12:15]
	v_mfma_f32_16x16x32_bf16 v[60:63], v[150:153], v[182:185], v[60:63]
	v_mfma_f32_16x16x32_bf16 v[56:59], v[158:161], v[182:185], v[56:59]
	v_mfma_f32_16x16x32_bf16 v[52:55], v[150:153], v[190:193], v[52:55]
	v_mfma_f32_16x16x32_bf16 v[44:47], v[158:161], v[190:193], v[44:47]
	v_mfma_f32_16x16x32_bf16 v[36:39], v[150:153], v[198:201], v[36:39]
	v_mfma_f32_16x16x32_bf16 v[32:35], v[158:161], v[198:201], v[32:35]
	v_mfma_f32_16x16x32_bf16 v[20:23], v[150:153], v[206:209], v[20:23]
	v_mfma_f32_16x16x32_bf16 v[12:15], v[158:161], v[206:209], v[12:15]
	s_setprio 0
	s_setprio 1
	v_mfma_f32_16x16x32_bf16 v[48:51], v[162:165], v[178:181], v[48:51]
	v_mfma_f32_16x16x32_bf16 v[40:43], v[170:173], v[178:181], v[40:43]
	v_mfma_f32_16x16x32_bf16 v[28:31], v[162:165], v[186:189], v[28:31]
	v_mfma_f32_16x16x32_bf16 v[24:27], v[170:173], v[186:189], v[24:27]
	v_mfma_f32_16x16x32_bf16 v[16:19], v[162:165], v[194:197], v[16:19]
	v_mfma_f32_16x16x32_bf16 v[8:11], v[170:173], v[194:197], v[8:11]
	v_mfma_f32_16x16x32_bf16 v[4:7], v[162:165], v[202:205], v[4:7]
	v_mfma_f32_16x16x32_bf16 v[0:3], v[170:173], v[202:205], v[0:3]
	v_mfma_f32_16x16x32_bf16 v[48:51], v[166:169], v[182:185], v[48:51]
	v_mfma_f32_16x16x32_bf16 v[40:43], v[174:177], v[182:185], v[40:43]
	v_mfma_f32_16x16x32_bf16 v[28:31], v[166:169], v[190:193], v[28:31]
	v_mfma_f32_16x16x32_bf16 v[24:27], v[174:177], v[190:193], v[24:27]
	v_mfma_f32_16x16x32_bf16 v[16:19], v[166:169], v[198:201], v[16:19]
	v_mfma_f32_16x16x32_bf16 v[8:11], v[174:177], v[198:201], v[8:11]
	v_mfma_f32_16x16x32_bf16 v[4:7], v[166:169], v[206:209], v[4:7]
	v_mfma_f32_16x16x32_bf16 v[0:3], v[174:177], v[206:209], v[0:3]
	s_setprio 0
	s_barrier
	s_add_i32 s82, s82, 2
	s_add_u32 s71, s71, 0x100
	s_addc_u32 s81, s81, 0
	s_add_u32 s10, s10, 0x100
	s_addc_u32 s11, s11, 0
	s_cmp_gt_u32 s82, 13
	s_cbranch_scc0 .LBB0_1719
	s_and_b64 vcc, exec, s[38:39]
	s_cbranch_vccz .LBB0_1722
	s_barrier

.LBB0_1835:
	ds_read_b128 v[144:147], v151
	ds_read_b128 v[154:157], v151 offset:1024
	ds_read_b128 v[158:161], v151 offset:2048
	ds_read_b128 v[162:165], v151 offset:3072
	ds_read_b128 v[166:169], v152
	ds_read_b128 v[170:173], v152 offset:1024
	ds_read_b128 v[174:177], v152 offset:2048
	ds_read_b128 v[178:181], v152 offset:3072
	s_add_u32 s40, s38, 0x100
	s_addc_u32 s41, s39, 0
	s_cmp_eq_u32 s62, 40
	s_cselect_b32 s45, s11, s41
	s_cselect_b32 s44, s10, s40
	s_cselect_b32 s43, s37, s27
	s_cselect_b32 s42, s36, s26
	s_add_i32 m0, s48, 0xc000
	ds_read_b128 v[182:185], v153
	ds_read_b128 v[186:189], v153 offset:1024
	ds_read_b128 v[190:193], v153 offset:2048
	ds_read_b128 v[194:197], v153 offset:3072
	ds_read_b128 v[198:201], v153 offset:4096
	ds_read_b128 v[202:205], v153 offset:5120
	ds_read_b128 v[206:209], v153 offset:6144
	ds_read_b128 v[210:213], v153 offset:7168
	global_load_lds_dwordx4 v138, s[38:39]
	s_add_i32 m0, s48, 0xe000
	s_nop 0
	global_load_lds_dwordx4 v136, s[38:39]
	s_waitcnt vmcnt(8)
	s_waitcnt lgkmcnt(0)
	s_barrier
	s_setprio 1
	s_waitcnt lgkmcnt(0)
	v_mfma_f32_16x16x32_bf16 v[124:127], v[144:147], v[182:185], v[124:127]
	v_mfma_f32_16x16x32_bf16 v[120:123], v[158:161], v[182:185], v[120:123]
	v_mfma_f32_16x16x32_bf16 v[108:111], v[144:147], v[190:193], v[108:111]
	v_mfma_f32_16x16x32_bf16 v[104:107], v[158:161], v[190:193], v[104:107]
	v_mfma_f32_16x16x32_bf16 v[92:95], v[144:147], v[198:201], v[92:95]
	v_mfma_f32_16x16x32_bf16 v[88:91], v[158:161], v[198:201], v[88:91]
	v_mfma_f32_16x16x32_bf16 v[76:79], v[144:147], v[206:209], v[76:79]
	v_mfma_f32_16x16x32_bf16 v[72:75], v[158:161], v[206:209], v[72:75]
	v_mfma_f32_16x16x32_bf16 v[124:127], v[154:157], v[186:189], v[124:127]
	v_mfma_f32_16x16x32_bf16 v[120:123], v[162:165], v[186:189], v[120:123]
	v_mfma_f32_16x16x32_bf16 v[108:111], v[154:157], v[194:197], v[108:111]
	v_mfma_f32_16x16x32_bf16 v[104:107], v[162:165], v[194:197], v[104:107]
	v_mfma_f32_16x16x32_bf16 v[92:95], v[154:157], v[202:205], v[92:95]
	v_mfma_f32_16x16x32_bf16 v[88:91], v[162:165], v[202:205], v[88:91]
	v_mfma_f32_16x16x32_bf16 v[76:79], v[154:157], v[210:213], v[76:79]
	v_mfma_f32_16x16x32_bf16 v[72:75], v[162:165], v[210:213], v[72:75]
	s_setprio 0
	s_setprio 1
	v_mfma_f32_16x16x32_bf16 v[116:119], v[166:169], v[182:185], v[116:119]
	v_mfma_f32_16x16x32_bf16 v[112:115], v[174:177], v[182:185], v[112:115]
	v_mfma_f32_16x16x32_bf16 v[100:103], v[166:169], v[190:193], v[100:103]
	v_mfma_f32_16x16x32_bf16 v[96:99], v[174:177], v[190:193], v[96:99]
	v_mfma_f32_16x16x32_bf16 v[84:87], v[166:169], v[198:201], v[84:87]
	v_mfma_f32_16x16x32_bf16 v[80:83], v[174:177], v[198:201], v[80:83]
	v_mfma_f32_16x16x32_bf16 v[68:71], v[166:169], v[206:209], v[68:71]
	v_mfma_f32_16x16x32_bf16 v[64:67], v[174:177], v[206:209], v[64:67]
	v_mfma_f32_16x16x32_bf16 v[116:119], v[170:173], v[186:189], v[116:119]
	v_mfma_f32_16x16x32_bf16 v[112:115], v[178:181], v[186:189], v[112:115]
	v_mfma_f32_16x16x32_bf16 v[100:103], v[170:173], v[194:197], v[100:103]
	v_mfma_f32_16x16x32_bf16 v[96:99], v[178:181], v[194:197], v[96:99]
	v_mfma_f32_16x16x32_bf16 v[84:87], v[170:173], v[202:205], v[84:87]
	v_mfma_f32_16x16x32_bf16 v[80:83], v[178:181], v[202:205], v[80:83]
	v_mfma_f32_16x16x32_bf16 v[68:71], v[170:173], v[210:213], v[68:71]
	v_mfma_f32_16x16x32_bf16 v[64:67], v[178:181], v[210:213], v[64:67]
	s_setprio 0
	s_barrier
	s_add_i32 s38, s57, s47
	v_lshl_add_u64 v[214:215], s[42:43], 0, v[130:131]
	s_mov_b32 m0, s38
	ds_read_b128 v[182:185], v153 offset:16384
	ds_read_b128 v[186:189], v153 offset:17408
	ds_read_b128 v[190:193], v153 offset:18432
	ds_read_b128 v[194:197], v153 offset:19456
	ds_read_b128 v[198:201], v153 offset:20480
	ds_read_b128 v[202:205], v153 offset:21504
	ds_read_b128 v[206:209], v153 offset:22528
	ds_read_b128 v[210:213], v153 offset:23552
	global_load_lds_dwordx4 v[214:215], off
	s_add_i32 m0, s38, 0x2000
	s_add_u32 s38, s42, 0xb0000
	v_lshl_add_u64 v[216:217], s[42:43], 0, v[134:135]
	s_addc_u32 s39, s43, 0
	s_add_i32 s63, s58, s47
	global_load_lds_dwordx4 v[216:217], off
	s_mov_b32 m0, s63
	v_lshl_add_u64 v[220:221], s[44:45], 0, v[132:133]
	global_load_lds_dwordx4 v130, s[38:39]
	s_add_i32 m0, s63, 0x2000
	s_nop 0
	global_load_lds_dwordx4 v134, s[38:39]
	v_lshl_add_u64 v[218:219], s[44:45], 0, v[128:129]
	s_mov_b32 m0, s48
	s_nop 0
	global_load_lds_dwordx4 v[218:219], off
	s_mov_b32 m0, s49
	s_nop 0
	global_load_lds_dwordx4 v[220:221], off
	s_waitcnt vmcnt(8)
	s_waitcnt lgkmcnt(0)
	s_barrier
	s_setprio 1
	s_waitcnt lgkmcnt(0)
	v_mfma_f32_16x16x32_bf16 v[60:63], v[144:147], v[182:185], v[60:63]
	v_mfma_f32_16x16x32_bf16 v[56:59], v[158:161], v[182:185], v[56:59]
	v_mfma_f32_16x16x32_bf16 v[44:47], v[144:147], v[190:193], v[44:47]
	v_mfma_f32_16x16x32_bf16 v[40:43], v[158:161], v[190:193], v[40:43]
	v_mfma_f32_16x16x32_bf16 v[28:31], v[144:147], v[198:201], v[28:31]
	v_mfma_f32_16x16x32_bf16 v[24:27], v[158:161], v[198:201], v[24:27]
	v_mfma_f32_16x16x32_bf16 v[12:15], v[144:147], v[206:209], v[12:15]
	v_mfma_f32_16x16x32_bf16 v[8:11], v[158:161], v[206:209], v[8:11]
	v_mfma_f32_16x16x32_bf16 v[60:63], v[154:157], v[186:189], v[60:63]
	v_mfma_f32_16x16x32_bf16 v[56:59], v[162:165], v[186:189], v[56:59]
	v_mfma_f32_16x16x32_bf16 v[44:47], v[154:157], v[194:197], v[44:47]
	v_mfma_f32_16x16x32_bf16 v[40:43], v[162:165], v[194:197], v[40:43]
	v_mfma_f32_16x16x32_bf16 v[28:31], v[154:157], v[202:205], v[28:31]
	v_mfma_f32_16x16x32_bf16 v[24:27], v[162:165], v[202:205], v[24:27]
	v_mfma_f32_16x16x32_bf16 v[12:15], v[154:157], v[210:213], v[12:15]
	v_mfma_f32_16x16x32_bf16 v[8:11], v[162:165], v[210:213], v[8:11]
	s_setprio 0
	s_setprio 1
	v_mfma_f32_16x16x32_bf16 v[52:55], v[166:169], v[182:185], v[52:55]
	v_mfma_f32_16x16x32_bf16 v[48:51], v[174:177], v[182:185], v[48:51]
	v_mfma_f32_16x16x32_bf16 v[36:39], v[166:169], v[190:193], v[36:39]
	v_mfma_f32_16x16x32_bf16 v[32:35], v[174:177], v[190:193], v[32:35]
	v_mfma_f32_16x16x32_bf16 v[20:23], v[166:169], v[198:201], v[20:23]
	v_mfma_f32_16x16x32_bf16 v[16:19], v[174:177], v[198:201], v[16:19]
	v_mfma_f32_16x16x32_bf16 v[4:7], v[166:169], v[206:209], v[4:7]
	v_mfma_f32_16x16x32_bf16 v[0:3], v[174:177], v[206:209], v[0:3]
	v_mfma_f32_16x16x32_bf16 v[52:55], v[170:173], v[186:189], v[52:55]
	v_mfma_f32_16x16x32_bf16 v[48:51], v[178:181], v[186:189], v[48:51]
	v_mfma_f32_16x16x32_bf16 v[36:39], v[170:173], v[194:197], v[36:39]
	v_mfma_f32_16x16x32_bf16 v[32:35], v[178:181], v[194:197], v[32:35]
	v_mfma_f32_16x16x32_bf16 v[20:23], v[170:173], v[202:205], v[20:23]
	v_mfma_f32_16x16x32_bf16 v[16:19], v[178:181], v[202:205], v[16:19]
	v_mfma_f32_16x16x32_bf16 v[4:7], v[170:173], v[210:213], v[4:7]
	v_mfma_f32_16x16x32_bf16 v[0:3], v[178:181], v[210:213], v[0:3]
	s_setprio 0
	s_barrier
	s_add_i32 s63, 0, 0x18000
	s_add_i32 s64, 0, 0x1c000
	v_add_u32_e32 v162, s63, v150
	v_add_u32_e32 v178, s64, v150
	ds_read_b128 v[144:147], v162
	ds_read_b128 v[154:157], v162 offset:1024
	ds_read_b128 v[158:161], v162 offset:2048
	ds_read_b128 v[162:165], v162 offset:3072
	ds_read_b128 v[166:169], v178
	ds_read_b128 v[170:173], v178 offset:1024
	ds_read_b128 v[174:177], v178 offset:2048
	ds_read_b128 v[178:181], v178 offset:3072
	s_add_u32 s38, s44, 0xb0000
	s_addc_u32 s39, s45, 0
	s_mov_b32 m0, s50
	ds_read_b128 v[182:185], v153 offset:32768
	ds_read_b128 v[186:189], v153 offset:33792
	ds_read_b128 v[190:193], v153 offset:34816
	ds_read_b128 v[194:197], v153 offset:35840
	ds_read_b128 v[198:201], v153 offset:36864
	ds_read_b128 v[202:205], v153 offset:37888
	ds_read_b128 v[206:209], v153 offset:38912
	ds_read_b128 v[210:213], v153 offset:39936
	global_load_lds_dwordx4 v128, s[38:39]
	s_mov_b32 m0, s51
	s_nop 0
	global_load_lds_dwordx4 v132, s[38:39]
	s_waitcnt vmcnt(8)
	s_waitcnt lgkmcnt(0)
	s_barrier
	s_setprio 1
	s_waitcnt lgkmcnt(0)
	v_mfma_f32_16x16x32_bf16 v[124:127], v[144:147], v[182:185], v[124:127]
	v_mfma_f32_16x16x32_bf16 v[120:123], v[158:161], v[182:185], v[120:123]
	v_mfma_f32_16x16x32_bf16 v[108:111], v[144:147], v[190:193], v[108:111]
	v_mfma_f32_16x16x32_bf16 v[104:107], v[158:161], v[190:193], v[104:107]
	v_mfma_f32_16x16x32_bf16 v[92:95], v[144:147], v[198:201], v[92:95]
	v_mfma_f32_16x16x32_bf16 v[88:91], v[158:161], v[198:201], v[88:91]
	v_mfma_f32_16x16x32_bf16 v[76:79], v[144:147], v[206:209], v[76:79]
	v_mfma_f32_16x16x32_bf16 v[72:75], v[158:161], v[206:209], v[72:75]
	v_mfma_f32_16x16x32_bf16 v[124:127], v[154:157], v[186:189], v[124:127]
	v_mfma_f32_16x16x32_bf16 v[120:123], v[162:165], v[186:189], v[120:123]
	v_mfma_f32_16x16x32_bf16 v[108:111], v[154:157], v[194:197], v[108:111]
	v_mfma_f32_16x16x32_bf16 v[104:107], v[162:165], v[194:197], v[104:107]
	v_mfma_f32_16x16x32_bf16 v[92:95], v[154:157], v[202:205], v[92:95]
	v_mfma_f32_16x16x32_bf16 v[88:91], v[162:165], v[202:205], v[88:91]
	v_mfma_f32_16x16x32_bf16 v[76:79], v[154:157], v[210:213], v[76:79]
	v_mfma_f32_16x16x32_bf16 v[72:75], v[162:165], v[210:213], v[72:75]
	s_setprio 0
	s_setprio 1
	v_mfma_f32_16x16x32_bf16 v[116:119], v[166:169], v[182:185], v[116:119]
	v_mfma_f32_16x16x32_bf16 v[112:115], v[174:177], v[182:185], v[112:115]
	v_mfma_f32_16x16x32_bf16 v[100:103], v[166:169], v[190:193], v[100:103]
	v_mfma_f32_16x16x32_bf16 v[96:99], v[174:177], v[190:193], v[96:99]
	v_mfma_f32_16x16x32_bf16 v[84:87], v[166:169], v[198:201], v[84:87]
	v_mfma_f32_16x16x32_bf16 v[80:83], v[174:177], v[198:201], v[80:83]
	v_mfma_f32_16x16x32_bf16 v[68:71], v[166:169], v[206:209], v[68:71]
	v_mfma_f32_16x16x32_bf16 v[64:67], v[174:177], v[206:209], v[64:67]
	v_mfma_f32_16x16x32_bf16 v[116:119], v[170:173], v[186:189], v[116:119]
	v_mfma_f32_16x16x32_bf16 v[112:115], v[178:181], v[186:189], v[112:115]
	v_mfma_f32_16x16x32_bf16 v[100:103], v[170:173], v[194:197], v[100:103]
	v_mfma_f32_16x16x32_bf16 v[96:99], v[178:181], v[194:197], v[96:99]
	v_mfma_f32_16x16x32_bf16 v[84:87], v[170:173], v[202:205], v[84:87]
	v_mfma_f32_16x16x32_bf16 v[80:83], v[178:181], v[202:205], v[80:83]
	v_mfma_f32_16x16x32_bf16 v[68:71], v[170:173], v[210:213], v[68:71]
	v_mfma_f32_16x16x32_bf16 v[64:67], v[178:181], v[210:213], v[64:67]
	s_setprio 0
	s_barrier
	s_add_i32 s38, s63, s47
	v_lshl_add_u64 v[214:215], v[214:215], 0, s[22:23]
	s_mov_b32 m0, s38
	ds_read_b128 v[182:185], v153 offset:49152
	ds_read_b128 v[186:189], v153 offset:50176
	ds_read_b128 v[190:193], v153 offset:51200
	ds_read_b128 v[194:197], v153 offset:52224
	ds_read_b128 v[198:201], v153 offset:53248
	ds_read_b128 v[202:205], v153 offset:54272
	ds_read_b128 v[206:209], v153 offset:55296
	ds_read_b128 v[210:213], v153 offset:56320
	global_load_lds_dwordx4 v[214:215], off
	s_add_i32 m0, s38, 0x2000
	s_add_u32 s38, s42, 0xb0080
	v_lshl_add_u64 v[214:215], v[216:217], 0, s[22:23]
	s_addc_u32 s39, s43, 0
	s_add_i32 s42, s64, s47
	global_load_lds_dwordx4 v[214:215], off
	s_mov_b32 m0, s42
	s_nop 0
	global_load_lds_dwordx4 v130, s[38:39]
	s_add_i32 m0, s42, 0x2000
	s_nop 0
	global_load_lds_dwordx4 v134, s[38:39]
	v_lshl_add_u64 v[214:215], v[218:219], 0, s[22:23]
	s_mov_b32 m0, s55
	s_nop 0
	global_load_lds_dwordx4 v[214:215], off
	v_lshl_add_u64 v[214:215], v[220:221], 0, s[22:23]
	s_mov_b32 m0, s56
	s_nop 0
	global_load_lds_dwordx4 v[214:215], off
	s_waitcnt vmcnt(8)
	s_waitcnt lgkmcnt(0)
	s_barrier
	s_setprio 1
	s_waitcnt lgkmcnt(0)
	v_mfma_f32_16x16x32_bf16 v[60:63], v[144:147], v[182:185], v[60:63]
	v_mfma_f32_16x16x32_bf16 v[56:59], v[158:161], v[182:185], v[56:59]
	v_mfma_f32_16x16x32_bf16 v[44:47], v[144:147], v[190:193], v[44:47]
	v_mfma_f32_16x16x32_bf16 v[40:43], v[158:161], v[190:193], v[40:43]
	v_mfma_f32_16x16x32_bf16 v[28:31], v[144:147], v[198:201], v[28:31]
	v_mfma_f32_16x16x32_bf16 v[24:27], v[158:161], v[198:201], v[24:27]
	v_mfma_f32_16x16x32_bf16 v[12:15], v[144:147], v[206:209], v[12:15]
	v_mfma_f32_16x16x32_bf16 v[8:11], v[158:161], v[206:209], v[8:11]
	v_mfma_f32_16x16x32_bf16 v[60:63], v[154:157], v[186:189], v[60:63]
	v_mfma_f32_16x16x32_bf16 v[56:59], v[162:165], v[186:189], v[56:59]
	v_mfma_f32_16x16x32_bf16 v[44:47], v[154:157], v[194:197], v[44:47]
	v_mfma_f32_16x16x32_bf16 v[40:43], v[162:165], v[194:197], v[40:43]
	v_mfma_f32_16x16x32_bf16 v[28:31], v[154:157], v[202:205], v[28:31]
	v_mfma_f32_16x16x32_bf16 v[24:27], v[162:165], v[202:205], v[24:27]
	v_mfma_f32_16x16x32_bf16 v[12:15], v[154:157], v[210:213], v[12:15]
	v_mfma_f32_16x16x32_bf16 v[8:11], v[162:165], v[210:213], v[8:11]
	s_setprio 0
	s_setprio 1
	v_mfma_f32_16x16x32_bf16 v[52:55], v[166:169], v[182:185], v[52:55]
	v_mfma_f32_16x16x32_bf16 v[48:51], v[174:177], v[182:185], v[48:51]
	v_mfma_f32_16x16x32_bf16 v[36:39], v[166:169], v[190:193], v[36:39]
	v_mfma_f32_16x16x32_bf16 v[32:35], v[174:177], v[190:193], v[32:35]
	v_mfma_f32_16x16x32_bf16 v[20:23], v[166:169], v[198:201], v[20:23]
	v_mfma_f32_16x16x32_bf16 v[16:19], v[174:177], v[198:201], v[16:19]
	v_mfma_f32_16x16x32_bf16 v[4:7], v[166:169], v[206:209], v[4:7]
	v_mfma_f32_16x16x32_bf16 v[0:3], v[174:177], v[206:209], v[0:3]
	v_mfma_f32_16x16x32_bf16 v[52:55], v[170:173], v[186:189], v[52:55]
	v_mfma_f32_16x16x32_bf16 v[48:51], v[178:181], v[186:189], v[48:51]
	v_mfma_f32_16x16x32_bf16 v[36:39], v[170:173], v[194:197], v[36:39]
	v_mfma_f32_16x16x32_bf16 v[32:35], v[178:181], v[194:197], v[32:35]
	v_mfma_f32_16x16x32_bf16 v[20:23], v[170:173], v[202:205], v[20:23]
	v_mfma_f32_16x16x32_bf16 v[16:19], v[178:181], v[202:205], v[16:19]
	v_mfma_f32_16x16x32_bf16 v[4:7], v[170:173], v[210:213], v[4:7]
	v_mfma_f32_16x16x32_bf16 v[0:3], v[178:181], v[210:213], v[0:3]
	s_setprio 0
	s_barrier
	s_add_i32 s62, s62, 2
	s_add_u32 s26, s26, 0x100
	s_addc_u32 s27, s27, 0
	s_cmp_gt_u32 s62, 41
	s_mov_b64 s[38:39], s[40:41]
	s_cbranch_scc0 .LBB0_1835
	s_and_b64 vcc, exec, s[34:35]
	s_cbranch_vccz .LBB0_1838
	s_barrier

.LBB0_1931:
	ds_read_b128 v[144:147], v181
	ds_read_b128 v[148:151], v181 offset:1024
	ds_read_b128 v[152:155], v181 offset:2048
	ds_read_b128 v[156:159], v181 offset:3072
	ds_read_b128 v[160:163], v182
	ds_read_b128 v[164:167], v182 offset:1024
	ds_read_b128 v[168:171], v182 offset:2048
	ds_read_b128 v[172:175], v182 offset:3072
	s_add_u32 s36, s34, 0x100
	s_addc_u32 s37, s35, 0
	s_cmp_eq_u32 s60, 40
	s_cselect_b32 s41, s7, s37
	s_cselect_b32 s40, s6, s36
	s_cselect_b32 s39, s31, s27
	s_cselect_b32 s38, s30, s16
	s_add_i32 m0, s42, 0xc000
	ds_read_b128 v[186:189], v183
	ds_read_b128 v[190:193], v183 offset:1024
	ds_read_b128 v[194:197], v183 offset:2048
	ds_read_b128 v[198:201], v183 offset:3072
	ds_read_b128 v[202:205], v183 offset:4096
	ds_read_b128 v[206:209], v183 offset:5120
	ds_read_b128 v[210:213], v183 offset:6144
	ds_read_b128 v[214:217], v183 offset:7168
	global_load_lds_dwordx4 v138, s[34:35]
	s_add_i32 m0, s42, 0xe000
	s_nop 0
	global_load_lds_dwordx4 v136, s[34:35]
	s_waitcnt vmcnt(8)
	s_waitcnt lgkmcnt(0)
	s_barrier
	s_setprio 1
	s_waitcnt lgkmcnt(0)
	v_mfma_f32_16x16x32_bf16 v[124:127], v[144:147], v[186:189], v[124:127]
	v_mfma_f32_16x16x32_bf16 v[120:123], v[152:155], v[186:189], v[120:123]
	v_mfma_f32_16x16x32_bf16 v[108:111], v[144:147], v[194:197], v[108:111]
	v_mfma_f32_16x16x32_bf16 v[104:107], v[152:155], v[194:197], v[104:107]
	v_mfma_f32_16x16x32_bf16 v[92:95], v[144:147], v[202:205], v[92:95]
	v_mfma_f32_16x16x32_bf16 v[88:91], v[152:155], v[202:205], v[88:91]
	v_mfma_f32_16x16x32_bf16 v[76:79], v[144:147], v[210:213], v[76:79]
	v_mfma_f32_16x16x32_bf16 v[72:75], v[152:155], v[210:213], v[72:75]
	v_mfma_f32_16x16x32_bf16 v[124:127], v[148:151], v[190:193], v[124:127]
	v_mfma_f32_16x16x32_bf16 v[120:123], v[156:159], v[190:193], v[120:123]
	v_mfma_f32_16x16x32_bf16 v[108:111], v[148:151], v[198:201], v[108:111]
	v_mfma_f32_16x16x32_bf16 v[104:107], v[156:159], v[198:201], v[104:107]
	v_mfma_f32_16x16x32_bf16 v[92:95], v[148:151], v[206:209], v[92:95]
	v_mfma_f32_16x16x32_bf16 v[88:91], v[156:159], v[206:209], v[88:91]
	v_mfma_f32_16x16x32_bf16 v[76:79], v[148:151], v[214:217], v[76:79]
	v_mfma_f32_16x16x32_bf16 v[72:75], v[156:159], v[214:217], v[72:75]
	s_setprio 0
	s_setprio 1
	v_mfma_f32_16x16x32_bf16 v[116:119], v[160:163], v[186:189], v[116:119]
	v_mfma_f32_16x16x32_bf16 v[112:115], v[168:171], v[186:189], v[112:115]
	v_mfma_f32_16x16x32_bf16 v[100:103], v[160:163], v[194:197], v[100:103]
	v_mfma_f32_16x16x32_bf16 v[96:99], v[168:171], v[194:197], v[96:99]
	v_mfma_f32_16x16x32_bf16 v[84:87], v[160:163], v[202:205], v[84:87]
	v_mfma_f32_16x16x32_bf16 v[80:83], v[168:171], v[202:205], v[80:83]
	v_mfma_f32_16x16x32_bf16 v[68:71], v[160:163], v[210:213], v[68:71]
	v_mfma_f32_16x16x32_bf16 v[64:67], v[168:171], v[210:213], v[64:67]
	v_mfma_f32_16x16x32_bf16 v[116:119], v[164:167], v[190:193], v[116:119]
	v_mfma_f32_16x16x32_bf16 v[112:115], v[172:175], v[190:193], v[112:115]
	v_mfma_f32_16x16x32_bf16 v[100:103], v[164:167], v[198:201], v[100:103]
	v_mfma_f32_16x16x32_bf16 v[96:99], v[172:175], v[198:201], v[96:99]
	v_mfma_f32_16x16x32_bf16 v[84:87], v[164:167], v[206:209], v[84:87]
	v_mfma_f32_16x16x32_bf16 v[80:83], v[172:175], v[206:209], v[80:83]
	v_mfma_f32_16x16x32_bf16 v[68:71], v[164:167], v[214:217], v[68:71]
	v_mfma_f32_16x16x32_bf16 v[64:67], v[172:175], v[214:217], v[64:67]
	s_setprio 0
	s_barrier
	s_add_i32 s34, s54, s25
	v_lshl_add_u64 v[176:177], s[38:39], 0, v[130:131]
	s_mov_b32 m0, s34
	ds_read_b128 v[186:189], v183 offset:16384
	ds_read_b128 v[190:193], v183 offset:17408
	ds_read_b128 v[194:197], v183 offset:18432
	ds_read_b128 v[198:201], v183 offset:19456
	ds_read_b128 v[202:205], v183 offset:20480
	ds_read_b128 v[206:209], v183 offset:21504
	ds_read_b128 v[210:213], v183 offset:22528
	ds_read_b128 v[214:217], v183 offset:23552
	global_load_lds_dwordx4 v[176:177], off
	s_add_i32 m0, s34, 0x2000
	s_add_u32 s34, s38, 0xb0000
	v_lshl_add_u64 v[218:219], s[38:39], 0, v[134:135]
	s_addc_u32 s35, s39, 0
	s_add_i32 s61, s55, s25
	global_load_lds_dwordx4 v[218:219], off
	s_mov_b32 m0, s61
	v_lshl_add_u64 v[222:223], s[40:41], 0, v[132:133]
	global_load_lds_dwordx4 v130, s[34:35]
	s_add_i32 m0, s61, 0x2000
	s_nop 0
	global_load_lds_dwordx4 v134, s[34:35]
	v_lshl_add_u64 v[220:221], s[40:41], 0, v[128:129]
	s_mov_b32 m0, s42
	s_nop 0
	global_load_lds_dwordx4 v[220:221], off
	s_mov_b32 m0, s43
	s_nop 0
	global_load_lds_dwordx4 v[222:223], off
	s_waitcnt vmcnt(8)
	s_waitcnt lgkmcnt(0)
	s_barrier
	s_setprio 1
	s_waitcnt lgkmcnt(0)
	v_mfma_f32_16x16x32_bf16 v[60:63], v[144:147], v[186:189], v[60:63]
	v_mfma_f32_16x16x32_bf16 v[56:59], v[152:155], v[186:189], v[56:59]
	v_mfma_f32_16x16x32_bf16 v[44:47], v[144:147], v[194:197], v[44:47]
	v_mfma_f32_16x16x32_bf16 v[40:43], v[152:155], v[194:197], v[40:43]
	v_mfma_f32_16x16x32_bf16 v[28:31], v[144:147], v[202:205], v[28:31]
	v_mfma_f32_16x16x32_bf16 v[24:27], v[152:155], v[202:205], v[24:27]
	v_mfma_f32_16x16x32_bf16 v[12:15], v[144:147], v[210:213], v[12:15]
	v_mfma_f32_16x16x32_bf16 v[8:11], v[152:155], v[210:213], v[8:11]
	v_mfma_f32_16x16x32_bf16 v[60:63], v[148:151], v[190:193], v[60:63]
	v_mfma_f32_16x16x32_bf16 v[56:59], v[156:159], v[190:193], v[56:59]
	v_mfma_f32_16x16x32_bf16 v[44:47], v[148:151], v[198:201], v[44:47]
	v_mfma_f32_16x16x32_bf16 v[40:43], v[156:159], v[198:201], v[40:43]
	v_mfma_f32_16x16x32_bf16 v[28:31], v[148:151], v[206:209], v[28:31]
	v_mfma_f32_16x16x32_bf16 v[24:27], v[156:159], v[206:209], v[24:27]
	v_mfma_f32_16x16x32_bf16 v[12:15], v[148:151], v[214:217], v[12:15]
	v_mfma_f32_16x16x32_bf16 v[8:11], v[156:159], v[214:217], v[8:11]
	s_setprio 0
	s_setprio 1
	v_mfma_f32_16x16x32_bf16 v[52:55], v[160:163], v[186:189], v[52:55]
	v_mfma_f32_16x16x32_bf16 v[48:51], v[168:171], v[186:189], v[48:51]
	v_mfma_f32_16x16x32_bf16 v[36:39], v[160:163], v[194:197], v[36:39]
	v_mfma_f32_16x16x32_bf16 v[32:35], v[168:171], v[194:197], v[32:35]
	v_mfma_f32_16x16x32_bf16 v[20:23], v[160:163], v[202:205], v[20:23]
	v_mfma_f32_16x16x32_bf16 v[16:19], v[168:171], v[202:205], v[16:19]
	v_mfma_f32_16x16x32_bf16 v[4:7], v[160:163], v[210:213], v[4:7]
	v_mfma_f32_16x16x32_bf16 v[0:3], v[168:171], v[210:213], v[0:3]
	v_mfma_f32_16x16x32_bf16 v[52:55], v[164:167], v[190:193], v[52:55]
	v_mfma_f32_16x16x32_bf16 v[48:51], v[172:175], v[190:193], v[48:51]
	v_mfma_f32_16x16x32_bf16 v[36:39], v[164:167], v[198:201], v[36:39]
	v_mfma_f32_16x16x32_bf16 v[32:35], v[172:175], v[198:201], v[32:35]
	v_mfma_f32_16x16x32_bf16 v[20:23], v[164:167], v[206:209], v[20:23]
	v_mfma_f32_16x16x32_bf16 v[16:19], v[172:175], v[206:209], v[16:19]
	v_mfma_f32_16x16x32_bf16 v[4:7], v[164:167], v[214:217], v[4:7]
	v_mfma_f32_16x16x32_bf16 v[0:3], v[172:175], v[214:217], v[0:3]
	s_setprio 0
	s_barrier
	s_add_i32 s61, 0, 0x18000
	s_add_i32 s62, 0, 0x1c000
	v_add_u32_e32 v156, s61, v180
	v_add_u32_e32 v172, s62, v180
	ds_read_b128 v[144:147], v156
	ds_read_b128 v[148:151], v156 offset:1024
	ds_read_b128 v[152:155], v156 offset:2048
	ds_read_b128 v[156:159], v156 offset:3072
	ds_read_b128 v[160:163], v172
	ds_read_b128 v[164:167], v172 offset:1024
	ds_read_b128 v[168:171], v172 offset:2048
	ds_read_b128 v[172:175], v172 offset:3072
	s_add_u32 s34, s40, 0xb0000
	s_addc_u32 s35, s41, 0
	s_mov_b32 m0, s44
	ds_read_b128 v[186:189], v183 offset:32768
	ds_read_b128 v[190:193], v183 offset:33792
	ds_read_b128 v[194:197], v183 offset:34816
	ds_read_b128 v[198:201], v183 offset:35840
	ds_read_b128 v[202:205], v183 offset:36864
	ds_read_b128 v[206:209], v183 offset:37888
	ds_read_b128 v[210:213], v183 offset:38912
	ds_read_b128 v[214:217], v183 offset:39936
	global_load_lds_dwordx4 v128, s[34:35]
	s_mov_b32 m0, s45
	s_nop 0
	global_load_lds_dwordx4 v132, s[34:35]
	s_waitcnt vmcnt(8)
	s_waitcnt lgkmcnt(0)
	s_barrier
	s_setprio 1
	s_waitcnt lgkmcnt(0)
	v_mfma_f32_16x16x32_bf16 v[124:127], v[144:147], v[186:189], v[124:127]
	v_mfma_f32_16x16x32_bf16 v[120:123], v[152:155], v[186:189], v[120:123]
	v_mfma_f32_16x16x32_bf16 v[108:111], v[144:147], v[194:197], v[108:111]
	v_mfma_f32_16x16x32_bf16 v[104:107], v[152:155], v[194:197], v[104:107]
	v_mfma_f32_16x16x32_bf16 v[92:95], v[144:147], v[202:205], v[92:95]
	v_mfma_f32_16x16x32_bf16 v[88:91], v[152:155], v[202:205], v[88:91]
	v_mfma_f32_16x16x32_bf16 v[76:79], v[144:147], v[210:213], v[76:79]
	v_mfma_f32_16x16x32_bf16 v[72:75], v[152:155], v[210:213], v[72:75]
	v_mfma_f32_16x16x32_bf16 v[124:127], v[148:151], v[190:193], v[124:127]
	v_mfma_f32_16x16x32_bf16 v[120:123], v[156:159], v[190:193], v[120:123]
	v_mfma_f32_16x16x32_bf16 v[108:111], v[148:151], v[198:201], v[108:111]
	v_mfma_f32_16x16x32_bf16 v[104:107], v[156:159], v[198:201], v[104:107]
	v_mfma_f32_16x16x32_bf16 v[92:95], v[148:151], v[206:209], v[92:95]
	v_mfma_f32_16x16x32_bf16 v[88:91], v[156:159], v[206:209], v[88:91]
	v_mfma_f32_16x16x32_bf16 v[76:79], v[148:151], v[214:217], v[76:79]
	v_mfma_f32_16x16x32_bf16 v[72:75], v[156:159], v[214:217], v[72:75]
	s_setprio 0
	s_setprio 1
	v_mfma_f32_16x16x32_bf16 v[116:119], v[160:163], v[186:189], v[116:119]
	v_mfma_f32_16x16x32_bf16 v[112:115], v[168:171], v[186:189], v[112:115]
	v_mfma_f32_16x16x32_bf16 v[100:103], v[160:163], v[194:197], v[100:103]
	v_mfma_f32_16x16x32_bf16 v[96:99], v[168:171], v[194:197], v[96:99]
	v_mfma_f32_16x16x32_bf16 v[84:87], v[160:163], v[202:205], v[84:87]
	v_mfma_f32_16x16x32_bf16 v[80:83], v[168:171], v[202:205], v[80:83]
	v_mfma_f32_16x16x32_bf16 v[68:71], v[160:163], v[210:213], v[68:71]
	v_mfma_f32_16x16x32_bf16 v[64:67], v[168:171], v[210:213], v[64:67]
	v_mfma_f32_16x16x32_bf16 v[116:119], v[164:167], v[190:193], v[116:119]
	v_mfma_f32_16x16x32_bf16 v[112:115], v[172:175], v[190:193], v[112:115]
	v_mfma_f32_16x16x32_bf16 v[100:103], v[164:167], v[198:201], v[100:103]
	v_mfma_f32_16x16x32_bf16 v[96:99], v[172:175], v[198:201], v[96:99]
	v_mfma_f32_16x16x32_bf16 v[84:87], v[164:167], v[206:209], v[84:87]
	v_mfma_f32_16x16x32_bf16 v[80:83], v[172:175], v[206:209], v[80:83]
	v_mfma_f32_16x16x32_bf16 v[68:71], v[164:167], v[214:217], v[68:71]
	v_mfma_f32_16x16x32_bf16 v[64:67], v[172:175], v[214:217], v[64:67]
	s_setprio 0
	s_barrier
	s_add_i32 s34, s61, s25
	v_lshl_add_u64 v[176:177], v[176:177], 0, s[20:21]
	s_mov_b32 m0, s34
	ds_read_b128 v[186:189], v183 offset:49152
	ds_read_b128 v[190:193], v183 offset:50176
	ds_read_b128 v[194:197], v183 offset:51200
	ds_read_b128 v[198:201], v183 offset:52224
	ds_read_b128 v[202:205], v183 offset:53248
	ds_read_b128 v[206:209], v183 offset:54272
	ds_read_b128 v[210:213], v183 offset:55296
	ds_read_b128 v[214:217], v183 offset:56320
	global_load_lds_dwordx4 v[176:177], off
	s_add_i32 m0, s34, 0x2000
	s_add_u32 s34, s38, 0xb0080
	v_lshl_add_u64 v[176:177], v[218:219], 0, s[20:21]
	s_addc_u32 s35, s39, 0
	s_add_i32 s38, s62, s25
	global_load_lds_dwordx4 v[176:177], off
	s_mov_b32 m0, s38
	s_nop 0
	global_load_lds_dwordx4 v130, s[34:35]
	s_add_i32 m0, s38, 0x2000
	s_nop 0
	global_load_lds_dwordx4 v134, s[34:35]
	v_lshl_add_u64 v[176:177], v[220:221], 0, s[20:21]
	s_mov_b32 m0, s51
	s_nop 0
	global_load_lds_dwordx4 v[176:177], off
	v_lshl_add_u64 v[176:177], v[222:223], 0, s[20:21]
	s_mov_b32 m0, s52
	s_nop 0
	global_load_lds_dwordx4 v[176:177], off
	s_waitcnt vmcnt(8)
	s_waitcnt lgkmcnt(0)
	s_barrier
	s_setprio 1
	s_waitcnt lgkmcnt(0)
	v_mfma_f32_16x16x32_bf16 v[60:63], v[144:147], v[186:189], v[60:63]
	v_mfma_f32_16x16x32_bf16 v[56:59], v[152:155], v[186:189], v[56:59]
	v_mfma_f32_16x16x32_bf16 v[44:47], v[144:147], v[194:197], v[44:47]
	v_mfma_f32_16x16x32_bf16 v[40:43], v[152:155], v[194:197], v[40:43]
	v_mfma_f32_16x16x32_bf16 v[28:31], v[144:147], v[202:205], v[28:31]
	v_mfma_f32_16x16x32_bf16 v[24:27], v[152:155], v[202:205], v[24:27]
	v_mfma_f32_16x16x32_bf16 v[12:15], v[144:147], v[210:213], v[12:15]
	v_mfma_f32_16x16x32_bf16 v[8:11], v[152:155], v[210:213], v[8:11]
	v_mfma_f32_16x16x32_bf16 v[60:63], v[148:151], v[190:193], v[60:63]
	v_mfma_f32_16x16x32_bf16 v[56:59], v[156:159], v[190:193], v[56:59]
	v_mfma_f32_16x16x32_bf16 v[44:47], v[148:151], v[198:201], v[44:47]
	v_mfma_f32_16x16x32_bf16 v[40:43], v[156:159], v[198:201], v[40:43]
	v_mfma_f32_16x16x32_bf16 v[28:31], v[148:151], v[206:209], v[28:31]
	v_mfma_f32_16x16x32_bf16 v[24:27], v[156:159], v[206:209], v[24:27]
	v_mfma_f32_16x16x32_bf16 v[12:15], v[148:151], v[214:217], v[12:15]
	v_mfma_f32_16x16x32_bf16 v[8:11], v[156:159], v[214:217], v[8:11]
	s_setprio 0
	s_setprio 1
	v_mfma_f32_16x16x32_bf16 v[52:55], v[160:163], v[186:189], v[52:55]
	v_mfma_f32_16x16x32_bf16 v[48:51], v[168:171], v[186:189], v[48:51]
	v_mfma_f32_16x16x32_bf16 v[36:39], v[160:163], v[194:197], v[36:39]
	v_mfma_f32_16x16x32_bf16 v[32:35], v[168:171], v[194:197], v[32:35]
	v_mfma_f32_16x16x32_bf16 v[20:23], v[160:163], v[202:205], v[20:23]
	v_mfma_f32_16x16x32_bf16 v[16:19], v[168:171], v[202:205], v[16:19]
	v_mfma_f32_16x16x32_bf16 v[4:7], v[160:163], v[210:213], v[4:7]
	v_mfma_f32_16x16x32_bf16 v[0:3], v[168:171], v[210:213], v[0:3]
	v_mfma_f32_16x16x32_bf16 v[52:55], v[164:167], v[190:193], v[52:55]
	v_mfma_f32_16x16x32_bf16 v[48:51], v[172:175], v[190:193], v[48:51]
	v_mfma_f32_16x16x32_bf16 v[36:39], v[164:167], v[198:201], v[36:39]
	v_mfma_f32_16x16x32_bf16 v[32:35], v[172:175], v[198:201], v[32:35]
	v_mfma_f32_16x16x32_bf16 v[20:23], v[164:167], v[206:209], v[20:23]
	v_mfma_f32_16x16x32_bf16 v[16:19], v[172:175], v[206:209], v[16:19]
	v_mfma_f32_16x16x32_bf16 v[4:7], v[164:167], v[214:217], v[4:7]
	v_mfma_f32_16x16x32_bf16 v[0:3], v[172:175], v[214:217], v[0:3]
	s_setprio 0
	s_barrier
	s_add_i32 s60, s60, 2
	s_add_u32 s16, s16, 0x100
	s_addc_u32 s27, s27, 0
	s_cmp_gt_u32 s60, 41
	s_mov_b64 s[34:35], s[36:37]
	s_cbranch_scc0 .LBB0_1931
	s_and_b64 vcc, exec, s[22:23]
	s_cbranch_vccz .LBB0_1934
	s_barrier
